# M1: DPP scans for the gate cumsum/max; k-row and v-row global loads hoisted to the q-load point (one load round trip per round instead of three)
# speedup vs baseline: 1.0080x; 1.0018x over previous
; __device__ __forceinline__ float wave_incl_sum(float v, int lane) {
; #pragma unroll
;     for (int o = 1; o < 64; o <<= 1) { const float t = __shfl_up(v, o); if (lane >= o) v += t; }
;     return v;
; }
; __device__ __forceinline__ float wave_incl_max(float v, int lane) {
; #pragma unroll
;     for (int o = 1; o < 64; o <<= 1) { const float t = __shfl_up(v, o); if (lane >= o) v = fmaxf(v, t); }
;     return v;
; }
; __device__ __forceinline__ float log_sigmoid_f(float x) { return fminf(x, 0.f) - log1pf(expf(-fabsf(x))); }
; __device__ __forceinline__ void m1_phase(const Params& p, unsigned char* ldsg, int G) {
;     ...
;         if (hw == 0) {
;             const float ig = GATES[(size_t)(t0 + lane) * 8 + h], fp = GATES[(size_t)(t0 + lane) * 8 + 4 + h];
;             const float b = wave_incl_sum(log_sigmoid_f(fp), lane);
;             const float g = __shfl(b, 63);
;             const float a = g - b + ig;
;             const float amax = wave_max(a);
;             sW[lane] = expf(a - amax);
;             if (lane == 0) { GARR[h * NCH + c] = g; AMAXARR[h * NCH + c] = amax; }
;         }
.LBB0_611:
	s_lshl_b32 s0, s82, 1
	s_ashr_i32 s83, s82, 1
	s_and_b32 s0, s0, 2
	s_add_i32 s44, s0, s2
	s_andn2_b64 vcc, exec, s[4:5]
	s_lshl_b32 s22, s83, 6
	s_cbranch_vccnz .LBB0_615
	v_or_b32_e32 v0, s22, v153
	v_ashrrev_i32_e32 v1, 31, v0
	v_lshlrev_b64 v[0:1], 5, v[0:1]
	s_ashr_i32 s45, s44, 31
	v_lshl_add_u64 v[0:1], s[54:55], 0, v[0:1]
	v_lshl_add_u64 v[0:1], s[44:45], 2, v[0:1]
	global_load_dword v2, v[0:1], off offset:16
	global_load_dword v5, v[0:1], off
	s_mov_b32 s0, 0xb2a5705f
	v_and_b32_e32 v3, 64, v144
	v_add_u32_e32 v4, -1, v144
	s_mov_b32 s1, 0x42ce8ed0
	v_cmp_lt_i32_e32 vcc, v4, v3
	s_mov_b32 s23, 0xc2b17218
	s_mov_b32 s24, 0x3f2aaaab
	v_cndmask_b32_e32 v4, v4, v144, vcc
	s_mov_b32 s25, 0x7f800000
	v_lshlrev_b32_e32 v4, 2, v4
	s_waitcnt vmcnt(1)
	v_mul_f32_e64 v0, |v2|, s3
	v_fma_f32 v1, |v2|, s3, -v0
	v_rndne_f32_e32 v6, v0
	v_fma_f32 v1, |v2|, s0, v1
	v_sub_f32_e32 v0, v0, v6
	v_add_f32_e32 v0, v0, v1
	v_cvt_i32_f32_e32 v6, v6
	v_exp_f32_e32 v0, v0
	v_cmp_ngt_f32_e64 vcc, |v2|, s1
	v_max_f32_e32 v1, v2, v2
	v_min_f32_e32 v7, 0, v1
	v_ldexp_f32 v0, v0, v6
	v_cndmask_b32_e32 v0, 0, v0, vcc
	v_cmp_nlt_f32_e64 vcc, |v2|, s23
	s_nop 1
	v_cndmask_b32_e32 v2, v143, v0, vcc
	v_add_f32_e32 v6, 1.0, v2
	v_add_f32_e32 v8, -1.0, v6
	v_frexp_mant_f32_e32 v9, v6
	v_cvt_f64_f32_e32 v[0:1], v6
	v_sub_f32_e32 v10, v8, v6
	v_frexp_exp_i32_f64_e32 v0, v[0:1]
	v_cmp_gt_f32_e32 vcc, s24, v9
	v_sub_f32_e32 v8, v2, v8
	v_add_f32_e32 v1, 1.0, v10
	v_subbrev_co_u32_e32 v0, vcc, 0, v0, vcc
	v_add_f32_e32 v1, v8, v1
	v_sub_u32_e32 v8, 0, v0
	v_cvt_f32_i32_e32 v0, v0
	v_ldexp_f32 v6, v6, v8
	v_ldexp_f32 v1, v1, v8
	v_add_f32_e32 v8, -1.0, v6
	v_add_f32_e32 v9, 1.0, v6
	v_add_f32_e32 v10, 1.0, v8
	v_add_f32_e32 v11, -1.0, v9
	v_sub_f32_e32 v10, v6, v10
	v_sub_f32_e32 v6, v6, v11
	v_mul_f32_e32 v11, 0x3f317218, v0
	v_add_f32_e32 v10, v1, v10
	v_add_f32_e32 v1, v1, v6
	v_fma_f32 v6, v0, s33, -v11
	v_add_f32_e32 v12, v8, v10
	v_add_f32_e32 v13, v9, v1
	v_fmac_f32_e32 v6, 0xb102e308, v0
	v_sub_f32_e32 v0, v8, v12
	v_sub_f32_e32 v8, v9, v13
	v_rcp_f32_e32 v9, v13
	v_add_f32_e32 v14, v11, v6
	v_add_f32_e32 v1, v1, v8
	v_sub_f32_e32 v8, v14, v11
	v_sub_f32_e32 v6, v6, v8
	v_mul_f32_e32 v8, v12, v9
	v_add_f32_e32 v0, v10, v0
	v_mul_f32_e32 v10, v13, v8
	v_fma_f32 v11, v8, v13, -v10
	v_fmac_f32_e32 v11, v8, v1
	v_add_f32_e32 v15, v10, v11
	v_sub_f32_e32 v16, v12, v15
	v_sub_f32_e32 v10, v15, v10
	v_sub_f32_e32 v12, v12, v16
	v_sub_f32_e32 v10, v10, v11
	v_sub_f32_e32 v11, v12, v15
	v_add_f32_e32 v0, v0, v11
	v_add_f32_e32 v0, v10, v0
	v_add_f32_e32 v10, v16, v0
	v_mul_f32_e32 v11, v9, v10
	v_sub_f32_e32 v12, v16, v10
	v_mul_f32_e32 v15, v13, v11
	v_add_f32_e32 v0, v0, v12
	v_add_f32_e32 v12, v8, v11
	v_fma_f32 v13, v11, v13, -v15
	v_sub_f32_e32 v8, v12, v8
	v_fmac_f32_e32 v13, v11, v1
	v_sub_f32_e32 v1, v11, v8
	v_add_f32_e32 v8, v15, v13
	v_sub_f32_e32 v11, v8, v15
	v_sub_f32_e32 v15, v10, v8
	v_sub_f32_e32 v10, v10, v15
	v_sub_f32_e32 v8, v10, v8
	v_sub_f32_e32 v11, v11, v13
	v_add_f32_e32 v0, v0, v8
	v_add_f32_e32 v0, v11, v0
	v_add_f32_e32 v0, v15, v0
	v_mul_f32_e32 v0, v9, v0
	v_add_f32_e32 v0, v1, v0
	v_add_f32_e32 v1, v12, v0
	v_mul_f32_e32 v8, v1, v1
	v_fmamk_f32 v11, v8, 0x3e9b6dac, v141
	v_sub_f32_e32 v9, v1, v12
	v_ldexp_f32 v10, v1, 1
	v_mul_f32_e32 v1, v1, v8
	v_fmaak_f32 v8, v8, v11, 0x3f2aaada
	v_mul_f32_e32 v1, v1, v8
	v_add_f32_e32 v8, v10, v1
	v_sub_f32_e32 v0, v0, v9
	v_sub_f32_e32 v9, v8, v10
	v_ldexp_f32 v0, v0, 1
	v_sub_f32_e32 v1, v1, v9
	v_add_f32_e32 v0, v0, v1
	v_add_f32_e32 v1, v8, v0
	v_sub_f32_e32 v8, v1, v8
	v_add_f32_e32 v9, v14, v1
	v_sub_f32_e32 v0, v0, v8
	v_sub_f32_e32 v8, v9, v14
	v_sub_f32_e32 v10, v9, v8
	v_sub_f32_e32 v1, v1, v8
	v_add_f32_e32 v8, v6, v0
	v_sub_f32_e32 v10, v14, v10
	v_sub_f32_e32 v11, v8, v6
	v_add_f32_e32 v1, v1, v10
	v_sub_f32_e32 v10, v8, v11
	v_sub_f32_e32 v0, v0, v11
	v_sub_f32_e32 v6, v6, v10
	v_add_f32_e32 v1, v8, v1
	v_add_f32_e32 v0, v0, v6
	v_add_f32_e32 v6, v9, v1
	v_sub_f32_e32 v8, v6, v9
	v_sub_f32_e32 v1, v1, v8
	v_add_f32_e32 v0, v0, v1
	v_add_f32_e32 v0, v6, v0
	v_cmp_neq_f32_e32 vcc, s25, v2
	s_nop 1
	v_cndmask_b32_e32 v0, v143, v0, vcc
	v_cmp_lt_f32_e64 vcc, |v2|, s43
	s_nop 1
	v_cndmask_b32_e32 v0, v0, v2, vcc
	v_sub_f32_e32 v0, v7, v0
	s_nop 1
	v_add_f32_dpp v0, v0, v0 row_shr:1 row_mask:0xf bank_mask:0xf bound_ctrl:0
	s_nop 1
	v_add_f32_dpp v0, v0, v0 row_shr:2 row_mask:0xf bank_mask:0xf bound_ctrl:0
	s_nop 1
	v_add_f32_dpp v0, v0, v0 row_shr:4 row_mask:0xf bank_mask:0xf bound_ctrl:0
	s_nop 1
	v_add_f32_dpp v0, v0, v0 row_shr:8 row_mask:0xf bank_mask:0xf bound_ctrl:0
	s_nop 1
	v_add_f32_dpp v0, v0, v0 row_bcast:15 row_mask:0xa bank_mask:0xf
	s_nop 1
	v_add_f32_dpp v0, v0, v0 row_bcast:31 row_mask:0xc bank_mask:0xf
	s_nop 1
	v_readlane_b32 s98, v0, 63
	s_waitcnt vmcnt(0)
	s_nop 1
	v_sub_f32_e32 v1, s98, v0
	v_add_f32_e32 v4, v5, v1
	v_mov_b32_e32 v1, v4
	s_nop 1
	v_max_f32_dpp v1, v1, v1 row_shr:1 row_mask:0xf bank_mask:0xf
	s_nop 1
	v_max_f32_dpp v1, v1, v1 row_shr:2 row_mask:0xf bank_mask:0xf
	s_nop 1
	v_max_f32_dpp v1, v1, v1 row_shr:4 row_mask:0xf bank_mask:0xf
	s_nop 1
	v_max_f32_dpp v1, v1, v1 row_shr:8 row_mask:0xf bank_mask:0xf
	s_nop 1
	v_max_f32_dpp v1, v1, v1 row_bcast:15 row_mask:0xa bank_mask:0xf
	s_nop 1
	v_max_f32_dpp v1, v1, v1 row_bcast:31 row_mask:0xc bank_mask:0xf
	s_nop 1
	v_readlane_b32 s99, v1, 63
	s_nop 2
	v_mov_b32_e32 v1, s99
	v_mov_b32_e32 v0, s98
	v_sub_f32_e32 v2, v4, v1
	v_mul_f32_e32 v3, 0x3fb8aa3b, v2
	v_fma_f32 v4, v2, s46, -v3
	v_rndne_f32_e32 v5, v3
	v_fmac_f32_e32 v4, 0x32a5705f, v2
	v_sub_f32_e32 v3, v3, v5
	v_add_f32_e32 v3, v3, v4
	v_cvt_i32_f32_e32 v5, v5
	v_exp_f32_e32 v3, v3
	v_cmp_ngt_f32_e32 vcc, s47, v2
	v_ldexp_f32 v3, v3, v5
	s_nop 0
	v_cndmask_b32_e32 v3, 0, v3, vcc
	v_cmp_nlt_f32_e32 vcc, s62, v2
	s_nop 1
	v_cndmask_b32_e32 v2, v143, v3, vcc
	ds_write_b32 v65, v2 offset:36864
	s_and_saveexec_b64 s[0:1], s[16:17]
	s_cbranch_execz .LBB0_614
	s_lshl_b32 s23, s44, 8
	s_add_i32 s24, s23, s83
	s_ashr_i32 s25, s24, 31
	s_lshl_b64 s[24:25], s[24:25], 2
	s_add_u32 s26, s34, s24
	s_addc_u32 s27, s35, s25
	s_add_u32 s24, s36, s24
	s_addc_u32 s25, s37, s25
	global_store_dword v67, v0, s[26:27]
	global_store_dword v67, v1, s[24:25]

; __device__ __forceinline__ u32x4 pack8(const float (&v)[8]) { u32x4 o; o.x = pk2(v[0], v[1]); o.y = pk2(v[2], v[3]); o.z = pk2(v[4], v[5]); o.w = pk2(v[6], v[7]); return o; }
; __device__ __forceinline__ void conv4x8(const bf16* proj, int t, int ch, const float* cw, const float* cb, float sc, float (&o)[4][8]) {
;     u32x4 raw[7];
; #pragma unroll
;     for (int i = 0; i < 7; ++i) { const int tr = t - 3 + i; raw[i] = tr >= 0 ? *(const u32x4*)(proj + (size_t)tr * NPROJ + ch) : (u32x4){0u, 0u, 0u, 0u}; }
;     { const f32x4 b0 = *(const f32x4*)(cb + ch), b1 = *(const f32x4*)(cb + ch + 4);
; #pragma unroll
;       for (int j = 0; j < 4; ++j) { o[j][0] = b0[0]; o[j][1] = b0[1]; o[j][2] = b0[2]; o[j][3] = b0[3]; o[j][4] = b1[0]; o[j][5] = b1[1]; o[j][6] = b1[2]; o[j][7] = b1[3]; } }
; #pragma unroll
;     for (int w = 0; w < 4; ++w) {
;         const f32x4 w0 = *(const f32x4*)(cw + w * 1024 + ch), w1 = *(const f32x4*)(cw + w * 1024 + ch + 4);
;         const float wv[8] = {w0[0], w0[1], w0[2], w0[3], w1[0], w1[1], w1[2], w1[3]};
; #pragma unroll
;         for (int j = 0; j < 4; ++j) { float xv[8]; unpack8(raw[j + w], xv);
; #pragma unroll
;             for (int e = 0; e < 8; ++e) o[j][e] += wv[e] * xv[e]; }
; __device__ __forceinline__ void m1_phase(const Params& p, unsigned char* ldsg, int G) {
;     ...
;             conv4x8(PROJ, t0 + l0, h * HD + cgp * 8, p.convw, p.convb, 1.0f, qv);
; #pragma unroll
;             for (int j = 0; j < 4; ++j) *(u32x4*)(QKC + (size_t)(t0 + l0 + j) * DM + h * HD + cgp * 8) = pack8(qv[j]);
;         }
;         asm volatile("" ::: "memory");
;         conv4x8(PROJ, t0 + l0, 512 + h * HD + cgp * 8, p.convw, p.convb, 0.08838834764831845f, kk);
; #pragma unroll
;         for (int j = 0; j < 4; ++j) *(u32x4*)(QKC + (size_t)(t0 + l0 + j) * DM + 512 + h * HD + cgp * 8) = pack8(kk[j]);
;         {
;             u32x4 rv[4];
; #pragma unroll
;             for (int j = 0; j < 4; ++j) rv[j] = *(const u32x4*)(PROJ + (size_t)(t0 + l0 + j) * NPROJ + 1024 + h * HD + cgp * 8);
.LBB0_630:
	s_or_b64 exec, exec, s[0:1]
	v_lshlrev_b64 v[10:11], 2, v[6:7]
	v_lshl_add_u64 v[12:13], s[50:51], 0, v[10:11]
	v_lshl_add_u64 v[42:43], s[48:49], 0, v[10:11]
	global_load_dwordx4 v[6:9], v[12:13], off offset:16
	global_load_dwordx4 v[14:17], v[12:13], off
	s_nop 0
	global_load_dwordx4 v[10:13], v[42:43], off offset:16
	global_load_dwordx4 v[18:21], v[42:43], off
	s_waitcnt vmcnt(4)
	v_lshlrev_b32_e32 v98, 16, v26
	v_and_b32_e32 v100, 0xffff0000, v26
	v_add_co_u32_e64 v26, s[0:1], s65, v42
	v_lshlrev_b32_e32 v99, 16, v27
	v_and_b32_e32 v101, 0xffff0000, v27
	v_lshlrev_b32_e32 v96, 16, v22
	v_and_b32_e32 v94, 0xffff0000, v22
	v_lshlrev_b32_e32 v97, 16, v23
	v_and_b32_e32 v95, 0xffff0000, v23
	v_lshl_add_u64 v[22:23], v[42:43], 0, s[6:7]
	v_addc_co_u32_e64 v27, s[0:1], 0, v43, s[0:1]
	v_lshlrev_b32_e32 v103, 16, v29
	v_lshlrev_b32_e32 v102, 16, v28
	v_and_b32_e32 v83, 0xffff0000, v29
	v_and_b32_e32 v82, 0xffff0000, v28
	v_lshlrev_b32_e32 v90, 16, v24
	v_and_b32_e32 v84, 0xffff0000, v24
	v_lshlrev_b32_e32 v91, 16, v25
	v_and_b32_e32 v85, 0xffff0000, v25
	global_load_dwordx4 v[34:37], v[26:27], off offset:-4096
	s_nop 0
	global_load_dwordx4 v[22:25], v[22:23], off offset:16
	v_lshl_add_u64 v[28:29], v[42:43], 0, s[38:39]
	v_lshl_add_u64 v[44:45], v[42:43], 0, s[40:41]
	v_add_co_u32_e64 v42, s[0:1], s80, v42
	global_load_dwordx4 v[38:41], v[26:27], off
	s_nop 0
	global_load_dwordx4 v[26:29], v[28:29], off offset:16
	v_addc_co_u32_e64 v43, s[0:1], 0, v43, s[0:1]
	global_load_dwordx4 v[46:49], v[42:43], off
	s_nop 0
	global_load_dwordx4 v[42:45], v[44:45], off offset:16
	s_ashr_i32 s59, s58, 31
	v_lshl_add_u64 v[62:63], s[58:59], 1, v[68:69]
	v_add_u32_e32 v248, s58, v119
	v_ashrrev_i32_e32 v249, 31, v248
	v_lshl_add_u64 v[248:249], v[248:249], 1, s[78:79]
	v_cmp_lt_i32_e64 s[98:99], 2, v74
	v_mov_b32_e32 v188, 0
	v_mov_b32_e32 v189, 0
	v_mov_b32_e32 v190, 0
	v_mov_b32_e32 v191, 0
	v_mov_b32_e32 v192, 0
	v_mov_b32_e32 v193, 0
	v_mov_b32_e32 v194, 0
	v_mov_b32_e32 v195, 0
	v_mov_b32_e32 v196, 0
	v_mov_b32_e32 v197, 0
	v_mov_b32_e32 v198, 0
	v_mov_b32_e32 v199, 0
	v_mov_b32_e32 v200, 0
	v_mov_b32_e32 v201, 0
	v_mov_b32_e32 v202, 0
	v_mov_b32_e32 v203, 0
	v_mov_b32_e32 v204, 0
	v_mov_b32_e32 v205, 0
	v_mov_b32_e32 v206, 0
	v_mov_b32_e32 v207, 0
	v_mov_b32_e32 v208, 0
	v_mov_b32_e32 v209, 0
	v_mov_b32_e32 v210, 0
	v_mov_b32_e32 v211, 0
	v_mov_b32_e32 v212, 0
	v_mov_b32_e32 v213, 0
	v_mov_b32_e32 v214, 0
	v_mov_b32_e32 v215, 0
	s_and_saveexec_b64 s[100:101], s[98:99]
	v_mad_u64_u32 v[238:239], s[84:85], v110, s63, v[248:249]
	global_load_dwordx4 v[188:191], v[238:239], off
	s_or_b64 exec, exec, s[100:101]
	s_and_saveexec_b64 s[100:101], s[22:23]
	v_mad_u64_u32 v[238:239], s[84:85], v111, s63, v[248:249]
	global_load_dwordx4 v[192:195], v[238:239], off
	s_or_b64 exec, exec, s[100:101]
	s_and_saveexec_b64 s[100:101], s[24:25]
	v_mad_u64_u32 v[238:239], s[84:85], v112, s63, v[248:249]
	global_load_dwordx4 v[196:199], v[238:239], off
	s_or_b64 exec, exec, s[100:101]
	s_and_saveexec_b64 s[100:101], s[60:61]
	v_mad_u64_u32 v[238:239], s[84:85], v74, s63, v[248:249]
	global_load_dwordx4 v[200:203], v[238:239], off
	s_or_b64 exec, exec, s[100:101]
	s_and_saveexec_b64 s[100:101], s[26:27]
	v_mad_u64_u32 v[238:239], s[84:85], v76, s63, v[248:249]
	global_load_dwordx4 v[204:207], v[238:239], off
	s_or_b64 exec, exec, s[100:101]
	s_and_saveexec_b64 s[100:101], s[28:29]
	v_mad_u64_u32 v[238:239], s[84:85], v78, s63, v[248:249]
	global_load_dwordx4 v[208:211], v[238:239], off
	s_or_b64 exec, exec, s[100:101]
	s_and_saveexec_b64 s[100:101], s[30:31]
	v_mad_u64_u32 v[238:239], s[84:85], v80, s63, v[248:249]
	global_load_dwordx4 v[212:215], v[238:239], off
	s_or_b64 exec, exec, s[100:101]
	v_lshl_add_u64 v[248:249], s[58:59], 1, v[66:67]
	v_lshl_add_u64 v[248:249], v[248:249], 0, s[78:79]
	v_mad_u64_u32 v[238:239], s[84:85], v74, s63, v[248:249]
	global_load_dwordx4 v[216:219], v[238:239], off offset:2048
	v_mad_u64_u32 v[238:239], s[84:85], v76, s63, v[248:249]
	global_load_dwordx4 v[220:223], v[238:239], off offset:2048
	v_mad_u64_u32 v[238:239], s[84:85], v78, s63, v[248:249]
	global_load_dwordx4 v[224:227], v[238:239], off offset:2048
	v_mad_u64_u32 v[238:239], s[84:85], v80, s63, v[248:249]
	global_load_dwordx4 v[250:253], v[238:239], off offset:2048
	s_waitcnt vmcnt(19)
	v_mov_b32_e32 v88, v14
	s_waitcnt vmcnt(17)
	v_mov_b32_e32 v86, v18
	v_mov_b32_e32 v87, v20
	v_mov_b32_e32 v89, v16
	v_mov_b32_e32 v20, v19
	v_mov_b32_e32 v16, v15
	v_pk_fma_f32 v[104:105], v[86:87], v[98:99], v[88:89]
	v_pk_fma_f32 v[106:107], v[20:21], v[100:101], v[16:17]
	v_lshlrev_b32_e32 v99, 16, v55
	v_lshlrev_b32_e32 v98, 16, v54
	v_and_b32_e32 v101, 0xffff0000, v55
	v_and_b32_e32 v100, 0xffff0000, v54
	v_lshlrev_b32_e32 v15, 16, v59
	v_lshlrev_b32_e32 v14, 16, v58
	v_and_b32_e32 v19, 0xffff0000, v59
	v_and_b32_e32 v18, 0xffff0000, v58
	s_waitcnt vmcnt(16)
	v_mov_b32_e32 v54, v34
	v_mov_b32_e32 v55, v36
	v_pk_fma_f32 v[58:59], v[54:55], v[96:97], v[104:105]
	v_mov_b32_e32 v36, v35
	v_pk_fma_f32 v[104:105], v[36:37], v[94:95], v[106:107]
	s_waitcnt vmcnt(14)
	v_mov_b32_e32 v34, v38
	v_mov_b32_e32 v35, v40
	v_pk_fma_f32 v[58:59], v[34:35], v[98:99], v[58:59]
	v_mov_b32_e32 v40, v39
	s_waitcnt vmcnt(12)
; __device__ __forceinline__ unsigned pk2(float lo, float hi) { return f2bf(lo) | (f2bf(hi) << 16); }
; __device__ __forceinline__ void conv4x8(const bf16* proj, int t, int ch, const float* cw, const float* cb, float sc, float (&o)[4][8]) {
;     ...
;         for (int j = 0; j < 4; ++j) { float xv[8]; unpack8(raw[j + w], xv);
; #pragma unroll
;             for (int e = 0; e < 8; ++e) o[j][e] += wv[e] * xv[e]; }
;     }
; #pragma unroll
;     for (int j = 0; j < 4; ++j)
; #pragma unroll
;         for (int e = 0; e < 8; ++e) o[j][e] = o[j][e] * sc * __builtin_amdgcn_rcpf(1.0f + __expf(-o[j][e]));
; }
; __device__ __forceinline__ u32x4 pack8(const float (&v)[8]) { u32x4 o; o.x = pk2(v[0], v[1]); o.y = pk2(v[2], v[3]); o.z = pk2(v[4], v[5]); o.w = pk2(v[6], v[7]); return o; }
; __device__ __forceinline__ void m1_phase(const Params& p, unsigned char* ldsg, int G) {
;     ...
;             conv4x8(PROJ, t0 + l0, h * HD + cgp * 8, p.convw, p.convb, 1.0f, qv);
; #pragma unroll
;             for (int j = 0; j < 4; ++j) *(u32x4*)(QKC + (size_t)(t0 + l0 + j) * DM + h * HD + cgp * 8) = pack8(qv[j]);
	v_mov_b32_e32 v38, v46
	v_mov_b32_e32 v39, v48
	v_pk_fma_f32 v[58:59], v[38:39], v[14:15], v[58:59]
	v_pk_fma_f32 v[104:105], v[40:41], v[100:101], v[104:105]
	v_mul_f32_e32 v1, 0xbfb8aa3b, v58
	v_exp_f32_e32 v1, v1
	v_mov_b32_e32 v48, v47
	v_pk_fma_f32 v[46:47], v[48:49], v[18:19], v[104:105]
	v_pk_fma_f32 v[94:95], v[20:21], v[94:95], v[16:17]
	v_add_f32_e32 v1, 1.0, v1
	v_rcp_f32_e32 v104, v1
	v_mul_f32_e32 v1, 0xbfb8aa3b, v46
	v_exp_f32_e32 v1, v1
	v_pk_fma_f32 v[94:95], v[36:37], v[100:101], v[94:95]
	v_add_f32_e32 v1, 1.0, v1
	v_rcp_f32_e32 v108, v1
	v_mul_f32_e32 v1, 0xbfb8aa3b, v59
	v_exp_f32_e32 v1, v1
	v_pk_fma_f32 v[94:95], v[40:41], v[18:19], v[94:95]
	v_add_f32_e32 v1, 1.0, v1
	v_rcp_f32_e32 v105, v1
	v_mul_f32_e32 v1, 0xbfb8aa3b, v47
	v_exp_f32_e32 v1, v1
	v_pk_mul_f32 v[106:107], v[58:59], v[104:105]
	v_mov_b32_e32 v58, v6
	v_add_f32_e32 v1, 1.0, v1
	v_rcp_f32_e32 v109, v1
	v_mov_b32_e32 v59, v8
	v_and_b32_e32 v105, 0xffff0000, v57
	v_and_b32_e32 v104, 0xffff0000, v56
	v_pk_mul_f32 v[108:109], v[46:47], v[108:109]
	v_mov_b32_e32 v46, v10
	v_mov_b32_e32 v47, v12
	v_pk_fma_f32 v[114:115], v[46:47], v[102:103], v[58:59]
	v_lshlrev_b32_e32 v103, 16, v57
	v_lshlrev_b32_e32 v102, 16, v56
	v_mov_b32_e32 v56, v22
	v_mov_b32_e32 v57, v24
	v_mov_b32_e32 v12, v11
	v_mov_b32_e32 v8, v7
	v_lshlrev_b32_e32 v7, 16, v61
	v_lshlrev_b32_e32 v6, 16, v60
	v_and_b32_e32 v11, 0xffff0000, v61
	v_and_b32_e32 v10, 0xffff0000, v60
	v_pk_fma_f32 v[60:61], v[56:57], v[90:91], v[114:115]
	v_mov_b32_e32 v24, v23
	v_mov_b32_e32 v22, v26
	v_mov_b32_e32 v23, v28
	v_pk_fma_f32 v[60:61], v[22:23], v[102:103], v[60:61]
	v_mov_b32_e32 v28, v27
	s_waitcnt vmcnt(11)
	v_mov_b32_e32 v26, v42
	v_mov_b32_e32 v27, v44
	v_pk_fma_f32 v[60:61], v[26:27], v[6:7], v[60:61]
	v_pk_fma_f32 v[82:83], v[12:13], v[82:83], v[8:9]
	v_mul_f32_e32 v1, 0xbfb8aa3b, v60
	v_exp_f32_e32 v1, v1
	v_pk_fma_f32 v[82:83], v[24:25], v[84:85], v[82:83]
	v_mov_b32_e32 v44, v43
	v_pk_fma_f32 v[82:83], v[28:29], v[104:105], v[82:83]
	v_add_f32_e32 v1, 1.0, v1
	v_pk_fma_f32 v[42:43], v[44:45], v[10:11], v[82:83]
	v_rcp_f32_e32 v82, v1
	v_mul_f32_e32 v1, 0xbfb8aa3b, v42
	v_exp_f32_e32 v1, v1
	v_bfe_u32 v77, v109, 16, 1
	v_add3_u32 v77, v109, v77, s81
	v_bfe_u32 v79, v108, 16, 1
	v_add_f32_e32 v1, 1.0, v1
	v_rcp_f32_e32 v114, v1
	v_mul_f32_e32 v1, 0xbfb8aa3b, v61
	v_exp_f32_e32 v1, v1
	v_add3_u32 v79, v108, v79, s81
	v_pk_fma_f32 v[90:91], v[46:47], v[90:91], v[58:59]
	v_pk_fma_f32 v[84:85], v[12:13], v[84:85], v[8:9]
	v_add_f32_e32 v1, 1.0, v1
	v_rcp_f32_e32 v83, v1
	v_mul_f32_e32 v1, 0xbfb8aa3b, v43
	v_exp_f32_e32 v1, v1
	v_pk_fma_f32 v[90:91], v[56:57], v[102:103], v[90:91]
	v_pk_mul_f32 v[60:61], v[60:61], v[82:83]
	v_pk_fma_f32 v[90:91], v[22:23], v[6:7], v[90:91]
	v_add_f32_e32 v1, 1.0, v1
	v_rcp_f32_e32 v115, v1
	v_bfe_u32 v81, v60, 16, 1
	v_bfe_u32 v82, v61, 16, 1
	v_add3_u32 v61, v61, v82, s81
	v_pk_mul_f32 v[42:43], v[42:43], v[114:115]
	v_add3_u32 v60, v60, v81, s81
	v_bfe_u32 v75, v42, 16, 1
	v_add3_u32 v42, v42, v75, s81
	v_bfe_u32 v75, v107, 16, 1
	v_bfe_u32 v1, v43, 16, 1
	v_add3_u32 v75, v107, v75, s81
	v_add3_u32 v1, v43, v1, s81
	v_bfe_u32 v43, v106, 16, 1
	v_lshrrev_b32_e32 v75, 16, v75
	v_add3_u32 v43, v106, v43, s81
	v_and_or_b32 v107, v77, s64, v75
	v_ashrrev_i32_e32 v75, 31, v74
	v_lshrrev_b32_e32 v43, 16, v43
	v_lshrrev_b32_e32 v60, 16, v60
	v_lshrrev_b32_e32 v61, 16, v61
	v_lshlrev_b64 v[82:83], 11, v[74:75]
	v_and_or_b32 v109, v1, s64, v61
	v_and_or_b32 v108, v42, s64, v60
	v_and_or_b32 v106, v79, s64, v43
	v_lshl_add_u64 v[42:43], v[62:63], 0, v[82:83]
	global_store_dwordx4 v[42:43], v[106:109], off
	v_pk_fma_f32 v[42:43], v[86:87], v[96:97], v[88:89]
	v_lshlrev_b32_e32 v61, 16, v51
	v_pk_fma_f32 v[42:43], v[54:55], v[98:99], v[42:43]
	v_lshlrev_b32_e32 v60, 16, v50
	v_pk_fma_f32 v[42:43], v[34:35], v[14:15], v[42:43]
	v_and_b32_e32 v51, 0xffff0000, v51
	v_pk_fma_f32 v[42:43], v[38:39], v[60:61], v[42:43]
	v_and_b32_e32 v50, 0xffff0000, v50
	v_mul_f32_e32 v1, 0xbfb8aa3b, v42
	v_exp_f32_e32 v1, v1
	v_pk_fma_f32 v[94:95], v[48:49], v[50:51], v[94:95]
	v_pk_fma_f32 v[84:85], v[24:25], v[104:105], v[84:85]
	v_add_f32_e32 v1, 1.0, v1
	v_rcp_f32_e32 v96, v1
	v_mul_f32_e32 v1, 0xbfb8aa3b, v94
	v_exp_f32_e32 v1, v1
	v_pk_fma_f32 v[84:85], v[28:29], v[10:11], v[84:85]
	v_add_f32_e32 v1, 1.0, v1
	v_rcp_f32_e32 v106, v1
	v_mul_f32_e32 v1, 0xbfb8aa3b, v43
	v_exp_f32_e32 v1, v1
	s_nop 0
	v_add_f32_e32 v1, 1.0, v1
	v_rcp_f32_e32 v97, v1
	v_mul_f32_e32 v1, 0xbfb8aa3b, v95
	v_exp_f32_e32 v1, v1
	v_pk_mul_f32 v[96:97], v[42:43], v[96:97]
	v_lshlrev_b32_e32 v43, 16, v53
	v_lshlrev_b32_e32 v42, 16, v52
	v_add_f32_e32 v1, 1.0, v1
	v_pk_fma_f32 v[90:91], v[26:27], v[42:43], v[90:91]
	v_rcp_f32_e32 v107, v1
	v_mul_f32_e32 v1, 0xbfb8aa3b, v90
	v_exp_f32_e32 v1, v1
	v_and_b32_e32 v53, 0xffff0000, v53
	v_and_b32_e32 v52, 0xffff0000, v52
	v_pk_fma_f32 v[84:85], v[44:45], v[52:53], v[84:85]
	v_add_f32_e32 v1, 1.0, v1
	v_pk_mul_f32 v[94:95], v[94:95], v[106:107]
	v_rcp_f32_e32 v106, v1
	v_mul_f32_e32 v1, 0xbfb8aa3b, v84
	v_exp_f32_e32 v1, v1
	v_bfe_u32 v77, v95, 16, 1
	v_bfe_u32 v79, v94, 16, 1
	v_add3_u32 v79, v94, v79, s81
	v_add_f32_e32 v1, 1.0, v1
	v_rcp_f32_e32 v108, v1
	v_mul_f32_e32 v1, 0xbfb8aa3b, v91
	v_exp_f32_e32 v1, v1
	v_add3_u32 v77, v95, v77, s81
	v_bfe_u32 v81, v96, 16, 1
	v_add3_u32 v81, v96, v81, s81
	v_add_f32_e32 v1, 1.0, v1
	v_rcp_f32_e32 v107, v1
	v_mul_f32_e32 v1, 0xbfb8aa3b, v85
	v_exp_f32_e32 v1, v1
	v_lshrrev_b32_e32 v81, 16, v81
	v_pk_mul_f32 v[90:91], v[90:91], v[106:107]
	v_add_f32_e32 v1, 1.0, v1
	v_rcp_f32_e32 v109, v1
	v_bfe_u32 v94, v91, 16, 1
	v_add3_u32 v91, v91, v94, s81
; __device__ __forceinline__ unsigned pk2(float lo, float hi) { return f2bf(lo) | (f2bf(hi) << 16); }
; __device__ __forceinline__ void conv4x8(const bf16* proj, int t, int ch, const float* cw, const float* cb, float sc, float (&o)[4][8]) {
;     ...
;         for (int j = 0; j < 4; ++j) { float xv[8]; unpack8(raw[j + w], xv);
; #pragma unroll
;             for (int e = 0; e < 8; ++e) o[j][e] += wv[e] * xv[e]; }
;     }
; #pragma unroll
;     for (int j = 0; j < 4; ++j)
; #pragma unroll
;         for (int e = 0; e < 8; ++e) o[j][e] = o[j][e] * sc * __builtin_amdgcn_rcpf(1.0f + __expf(-o[j][e]));
; }
; __device__ __forceinline__ u32x4 pack8(const float (&v)[8]) { u32x4 o; o.x = pk2(v[0], v[1]); o.y = pk2(v[2], v[3]); o.z = pk2(v[4], v[5]); o.w = pk2(v[6], v[7]); return o; }
; __device__ __forceinline__ void m1_phase(const Params& p, unsigned char* ldsg, int G) {
;     ...
;             conv4x8(PROJ, t0 + l0, h * HD + cgp * 8, p.convw, p.convb, 1.0f, qv);
; #pragma unroll
;             for (int j = 0; j < 4; ++j) *(u32x4*)(QKC + (size_t)(t0 + l0 + j) * DM + h * HD + cgp * 8) = pack8(qv[j]);
	v_and_or_b32 v94, v79, s64, v81
	v_pk_mul_f32 v[84:85], v[84:85], v[108:109]
	s_nop 0
	v_bfe_u32 v75, v84, 16, 1
	v_bfe_u32 v1, v85, 16, 1
	v_add3_u32 v75, v84, v75, s81
	v_bfe_u32 v84, v97, 16, 1
	v_add3_u32 v1, v85, v1, s81
	v_bfe_u32 v85, v90, 16, 1
	v_add3_u32 v84, v97, v84, s81
	v_add3_u32 v85, v90, v85, s81
	v_lshrrev_b32_e32 v84, 16, v84
	v_lshrrev_b32_e32 v85, 16, v85
	v_and_or_b32 v95, v77, s64, v84
	v_ashrrev_i32_e32 v77, 31, v76
	v_lshrrev_b32_e32 v90, 16, v91
	v_and_or_b32 v96, v75, s64, v85
	v_lshlrev_b64 v[84:85], 11, v[76:77]
	v_and_or_b32 v97, v1, s64, v90
	v_lshl_add_u64 v[90:91], v[62:63], 0, v[84:85]
	global_store_dwordx4 v[90:91], v[94:97], off
	v_pk_fma_f32 v[90:91], v[20:21], v[100:101], v[16:17]
	v_pk_fma_f32 v[16:17], v[20:21], v[18:19], v[16:17]
	v_lshlrev_b32_e32 v95, 16, v31
	v_lshlrev_b32_e32 v94, 16, v30
	v_and_b32_e32 v97, 0xffff0000, v31
	v_and_b32_e32 v96, 0xffff0000, v30
	v_pk_fma_f32 v[30:31], v[86:87], v[98:99], v[88:89]
	v_pk_fma_f32 v[90:91], v[36:37], v[18:19], v[90:91]
	v_pk_fma_f32 v[30:31], v[54:55], v[14:15], v[30:31]
	v_pk_fma_f32 v[90:91], v[40:41], v[50:51], v[90:91]
	v_pk_fma_f32 v[30:31], v[34:35], v[60:61], v[30:31]
	v_pk_fma_f32 v[90:91], v[48:49], v[96:97], v[90:91]
	v_pk_fma_f32 v[30:31], v[38:39], v[94:95], v[30:31]
	v_pk_fma_f32 v[14:15], v[86:87], v[14:15], v[88:89]
	v_mul_f32_e32 v1, 0xbfb8aa3b, v30
	v_exp_f32_e32 v1, v1
	v_pk_fma_f32 v[14:15], v[54:55], v[60:61], v[14:15]
	v_pk_fma_f32 v[16:17], v[36:37], v[50:51], v[16:17]
	v_pk_fma_f32 v[14:15], v[34:35], v[94:95], v[14:15]
	v_add_f32_e32 v1, 1.0, v1
	v_rcp_f32_e32 v98, v1
	v_mul_f32_e32 v1, 0xbfb8aa3b, v90
	v_exp_f32_e32 v1, v1
	v_pk_fma_f32 v[16:17], v[40:41], v[96:97], v[16:17]
	v_add_f32_e32 v1, 1.0, v1
	v_rcp_f32_e32 v100, v1
	v_mul_f32_e32 v1, 0xbfb8aa3b, v31
	v_exp_f32_e32 v1, v1
	s_nop 0
	v_add_f32_e32 v1, 1.0, v1
	v_rcp_f32_e32 v99, v1
	v_mul_f32_e32 v1, 0xbfb8aa3b, v91
	v_exp_f32_e32 v1, v1
	v_pk_mul_f32 v[30:31], v[30:31], v[98:99]
	v_lshlrev_b32_e32 v99, 16, v33
	v_add_f32_e32 v1, 1.0, v1
	v_rcp_f32_e32 v101, v1
	v_lshlrev_b32_e32 v98, 16, v32
	v_bfe_u32 v81, v30, 16, 1
	v_add3_u32 v30, v30, v81, s81
	v_pk_mul_f32 v[90:91], v[90:91], v[100:101]
	v_and_b32_e32 v101, 0xffff0000, v33
	v_and_b32_e32 v100, 0xffff0000, v32
	v_pk_fma_f32 v[32:33], v[46:47], v[102:103], v[58:59]
	v_pk_fma_f32 v[102:103], v[12:13], v[104:105], v[8:9]
	v_pk_fma_f32 v[32:33], v[56:57], v[6:7], v[32:33]
	v_pk_fma_f32 v[102:103], v[24:25], v[10:11], v[102:103]
	v_pk_fma_f32 v[32:33], v[22:23], v[42:43], v[32:33]
	v_pk_fma_f32 v[102:103], v[28:29], v[52:53], v[102:103]
	v_pk_fma_f32 v[32:33], v[26:27], v[98:99], v[32:33]
	v_pk_fma_f32 v[102:103], v[44:45], v[100:101], v[102:103]
	v_mul_f32_e32 v1, 0xbfb8aa3b, v32
	v_exp_f32_e32 v1, v1
	v_bfe_u32 v77, v91, 16, 1
	v_bfe_u32 v79, v90, 16, 1
	v_add3_u32 v79, v90, v79, s81
	v_add_f32_e32 v1, 1.0, v1
	v_rcp_f32_e32 v104, v1
	v_mul_f32_e32 v1, 0xbfb8aa3b, v102
	v_exp_f32_e32 v1, v1
	v_add3_u32 v77, v91, v77, s81
	v_bfe_u32 v90, v31, 16, 1
	v_lshrrev_b32_e32 v30, 16, v30
	v_add_f32_e32 v1, 1.0, v1
	v_rcp_f32_e32 v106, v1
	v_mul_f32_e32 v1, 0xbfb8aa3b, v33
	v_exp_f32_e32 v1, v1
	v_add3_u32 v31, v31, v90, s81
	v_and_or_b32 v30, v79, s64, v30
	v_ashrrev_i32_e32 v79, 31, v78
	v_add_f32_e32 v1, 1.0, v1
	v_rcp_f32_e32 v105, v1
	v_mul_f32_e32 v1, 0xbfb8aa3b, v103
	v_exp_f32_e32 v1, v1
	v_lshrrev_b32_e32 v31, 16, v31
	v_pk_mul_f32 v[32:33], v[32:33], v[104:105]
	v_and_or_b32 v31, v77, s64, v31
	v_add_f32_e32 v1, 1.0, v1
	v_rcp_f32_e32 v107, v1
	v_bfe_u32 v91, v32, 16, 1
	v_add3_u32 v32, v32, v91, s81
	v_lshrrev_b32_e32 v32, 16, v32
	v_pk_mul_f32 v[102:103], v[102:103], v[106:107]
	v_lshlrev_b64 v[90:91], 11, v[78:79]
	v_bfe_u32 v75, v102, 16, 1
	v_add3_u32 v75, v102, v75, s81
	v_bfe_u32 v102, v33, 16, 1
	v_bfe_u32 v1, v103, 16, 1
	v_add3_u32 v33, v33, v102, s81
	v_add3_u32 v1, v103, v1, s81
	v_lshrrev_b32_e32 v33, 16, v33
	v_and_or_b32 v33, v1, s64, v33
	v_and_or_b32 v32, v75, s64, v32
	v_lshl_add_u64 v[102:103], v[62:63], 0, v[90:91]
	global_store_dwordx4 v[102:103], v[30:33], off
	v_pk_fma_f32 v[6:7], v[46:47], v[6:7], v[58:59]
	v_pk_fma_f32 v[8:9], v[12:13], v[10:11], v[8:9]
	v_lshlrev_b32_e32 v31, 16, v3
	v_lshlrev_b32_e32 v30, 16, v2
	v_pk_fma_f32 v[14:15], v[38:39], v[30:31], v[14:15]
	v_and_b32_e32 v3, 0xffff0000, v3
	v_mul_f32_e32 v1, 0xbfb8aa3b, v14
	v_exp_f32_e32 v1, v1
	v_and_b32_e32 v2, 0xffff0000, v2
	v_pk_fma_f32 v[2:3], v[48:49], v[2:3], v[16:17]
	v_pk_fma_f32 v[6:7], v[56:57], v[42:43], v[6:7]
	v_add_f32_e32 v1, 1.0, v1
	v_rcp_f32_e32 v16, v1
	v_mul_f32_e32 v1, 0xbfb8aa3b, v2
	v_exp_f32_e32 v1, v1
	v_pk_fma_f32 v[6:7], v[22:23], v[98:99], v[6:7]
	v_pk_fma_f32 v[8:9], v[24:25], v[52:53], v[8:9]
	v_ashrrev_i32_e32 v81, 31, v80
	v_add_f32_e32 v1, 1.0, v1
	v_rcp_f32_e32 v18, v1
	v_mul_f32_e32 v1, 0xbfb8aa3b, v15
	v_exp_f32_e32 v1, v1
	v_pk_fma_f32 v[8:9], v[28:29], v[100:101], v[8:9]
	v_lshlrev_b64 v[86:87], 11, v[80:81]
	v_add_f32_e32 v1, 1.0, v1
	v_rcp_f32_e32 v17, v1
	v_mul_f32_e32 v1, 0xbfb8aa3b, v3
	v_exp_f32_e32 v1, v1
	v_pk_mul_f32 v[14:15], v[14:15], v[16:17]
	v_lshlrev_b32_e32 v17, 16, v5
	v_lshlrev_b32_e32 v16, 16, v4
	v_add_f32_e32 v1, 1.0, v1
	v_pk_fma_f32 v[6:7], v[26:27], v[16:17], v[6:7]
	v_rcp_f32_e32 v19, v1
	v_mul_f32_e32 v1, 0xbfb8aa3b, v6
	v_exp_f32_e32 v1, v1
	v_and_b32_e32 v5, 0xffff0000, v5
	v_and_b32_e32 v4, 0xffff0000, v4
	v_pk_fma_f32 v[4:5], v[44:45], v[4:5], v[8:9]
	v_add_f32_e32 v1, 1.0, v1
	v_rcp_f32_e32 v8, v1
	v_mul_f32_e32 v1, 0xbfb8aa3b, v4
	v_exp_f32_e32 v1, v1
	v_pk_mul_f32 v[2:3], v[2:3], v[18:19]
	v_add_f32_e32 v1, 1.0, v1
	v_rcp_f32_e32 v10, v1
; __device__ __forceinline__ u32x4 pack8(const float (&v)[8]) { u32x4 o; o.x = pk2(v[0], v[1]); o.y = pk2(v[2], v[3]); o.z = pk2(v[4], v[5]); o.w = pk2(v[6], v[7]); return o; }
; __device__ __forceinline__ void conv4x8(const bf16* proj, int t, int ch, const float* cw, const float* cb, float sc, float (&o)[4][8]) {
;     u32x4 raw[7];
; #pragma unroll
;     for (int i = 0; i < 7; ++i) { const int tr = t - 3 + i; raw[i] = tr >= 0 ? *(const u32x4*)(proj + (size_t)tr * NPROJ + ch) : (u32x4){0u, 0u, 0u, 0u}; }
;     { const f32x4 b0 = *(const f32x4*)(cb + ch), b1 = *(const f32x4*)(cb + ch + 4);
; #pragma unroll
;       for (int j = 0; j < 4; ++j) { o[j][0] = b0[0]; o[j][1] = b0[1]; o[j][2] = b0[2]; o[j][3] = b0[3]; o[j][4] = b1[0]; o[j][5] = b1[1]; o[j][6] = b1[2]; o[j][7] = b1[3]; } }
; #pragma unroll
;     for (int w = 0; w < 4; ++w) {
;         const f32x4 w0 = *(const f32x4*)(cw + w * 1024 + ch), w1 = *(const f32x4*)(cw + w * 1024 + ch + 4);
;         const float wv[8] = {w0[0], w0[1], w0[2], w0[3], w1[0], w1[1], w1[2], w1[3]};
; #pragma unroll
;         for (int j = 0; j < 4; ++j) { float xv[8]; unpack8(raw[j + w], xv);
; #pragma unroll
;             for (int e = 0; e < 8; ++e) o[j][e] += wv[e] * xv[e]; }
; __device__ __forceinline__ void m1_phase(const Params& p, unsigned char* ldsg, int G) {
;     ...
;             conv4x8(PROJ, t0 + l0, h * HD + cgp * 8, p.convw, p.convb, 1.0f, qv);
; #pragma unroll
;             for (int j = 0; j < 4; ++j) *(u32x4*)(QKC + (size_t)(t0 + l0 + j) * DM + h * HD + cgp * 8) = pack8(qv[j]);
;         }
;         asm volatile("" ::: "memory");
;         conv4x8(PROJ, t0 + l0, 512 + h * HD + cgp * 8, p.convw, p.convb, 0.08838834764831845f, kk);
	v_mul_f32_e32 v1, 0xbfb8aa3b, v7
	v_exp_f32_e32 v1, v1
	s_nop 0
	v_add_f32_e32 v1, 1.0, v1
	v_rcp_f32_e32 v9, v1
	v_mul_f32_e32 v1, 0xbfb8aa3b, v5
	v_exp_f32_e32 v1, v1
	v_pk_mul_f32 v[6:7], v[6:7], v[8:9]
	v_bfe_u32 v9, v3, 16, 1
	v_add_f32_e32 v1, 1.0, v1
	v_rcp_f32_e32 v11, v1
	v_add3_u32 v3, v3, v9, s81
	v_bfe_u32 v9, v6, 16, 1
	v_add3_u32 v6, v6, v9, s81
	v_pk_mul_f32 v[4:5], v[4:5], v[10:11]
	v_bfe_u32 v10, v2, 16, 1
	v_bfe_u32 v1, v5, 16, 1
	v_bfe_u32 v8, v4, 16, 1
	v_add3_u32 v2, v2, v10, s81
	v_add3_u32 v4, v4, v8, s81
	v_add3_u32 v1, v5, v1, s81
	v_bfe_u32 v5, v14, 16, 1
	v_bfe_u32 v8, v15, 16, 1
	v_bfe_u32 v10, v7, 16, 1
	v_add3_u32 v7, v7, v10, s81
	v_add3_u32 v8, v15, v8, s81
	v_add3_u32 v5, v14, v5, s81
	v_lshrrev_b32_e32 v9, 16, v5
	v_lshrrev_b32_e32 v8, 16, v8
	v_lshrrev_b32_e32 v6, 16, v6
	v_lshrrev_b32_e32 v5, 16, v7
	v_and_or_b32 v5, v1, s64, v5
	v_and_or_b32 v4, v4, s64, v6
	v_and_or_b32 v3, v3, s64, v8
	v_and_or_b32 v2, v2, s64, v9
	v_lshl_add_u64 v[6:7], v[62:63], 0, v[86:87]
	global_store_dwordx4 v[6:7], v[2:5], off
	v_add_u32_e32 v8, s58, v119
	v_ashrrev_i32_e32 v9, 31, v8
	v_lshlrev_b64 v[12:13], 2, v[8:9]
	v_lshl_add_u64 v[32:33], s[48:49], 0, v[12:13]
	v_add_co_u32_e32 v28, vcc, s65, v32
	v_lshl_add_u64 v[12:13], s[50:51], 0, v[12:13]
	s_nop 0
	v_addc_co_u32_e32 v29, vcc, 0, v33, vcc
	global_load_dwordx4 v[16:19], v[32:33], off
	global_load_dwordx4 v[8:11], v[32:33], off offset:16
	global_load_dwordx4 v[20:23], v[12:13], off
	s_nop 0
	global_load_dwordx4 v[12:15], v[12:13], off offset:16
	s_nop 0
	global_load_dwordx4 v[36:39], v[28:29], off offset:-4096
	global_load_dwordx4 v[40:43], v[28:29], off
	v_add_co_u32_e32 v28, vcc, s80, v32
	s_waitcnt vmcnt(6)
	v_lshlrev_b32_e32 v95, 16, v189
	v_addc_co_u32_e32 v29, vcc, 0, v33, vcc
	global_load_dwordx4 v[44:47], v[28:29], off
	v_lshlrev_b32_e32 v94, 16, v188
	v_and_b32_e32 v97, 0xffff0000, v189
	v_and_b32_e32 v96, 0xffff0000, v188
	v_lshl_add_u64 v[0:1], v[32:33], 0, s[6:7]
	global_load_dwordx4 v[28:31], v[0:1], off offset:16
	v_lshl_add_u64 v[0:1], v[32:33], 0, s[38:39]
	v_lshlrev_b32_e32 v101, 16, v191
	v_lshlrev_b32_e32 v100, 16, v190
	v_and_b32_e32 v107, 0xffff0000, v191
	v_and_b32_e32 v106, 0xffff0000, v190
	global_load_dwordx4 v[0:3], v[0:1], off offset:16
	v_lshl_add_u64 v[32:33], v[32:33], 0, s[40:41]
	global_load_dwordx4 v[32:35], v[32:33], off offset:16
	v_lshlrev_b32_e32 v117, 16, v193
	v_lshlrev_b32_e32 v116, 16, v192
	v_and_b32_e32 v177, 0xffff0000, v193
	v_and_b32_e32 v176, 0xffff0000, v192
	v_lshlrev_b32_e32 v113, 16, v195
	v_lshlrev_b32_e32 v112, 16, v194
	v_and_b32_e32 v115, 0xffff0000, v195
	v_and_b32_e32 v114, 0xffff0000, v194
	v_lshlrev_b32_e32 v110, 16, v196
	v_and_b32_e32 v108, 0xffff0000, v196
	v_lshlrev_b32_e32 v111, 16, v197
	v_and_b32_e32 v109, 0xffff0000, v197
	v_lshlrev_b32_e32 v104, 16, v198
	v_and_b32_e32 v102, 0xffff0000, v198
	v_lshlrev_b32_e32 v105, 16, v199
	v_and_b32_e32 v103, 0xffff0000, v199
	v_lshlrev_b32_e32 v57, 16, v201
	v_lshlrev_b32_e32 v56, 16, v200
	v_and_b32_e32 v59, 0xffff0000, v201
	v_and_b32_e32 v58, 0xffff0000, v200
	s_lshl_b64 s[0:1], s[58:59], 1
	v_lshl_add_u64 v[84:85], s[56:57], 0, v[84:85]
	v_lshl_add_u64 v[84:85], v[84:85], 0, s[0:1]
	v_lshl_add_u64 v[84:85], v[84:85], 0, v[66:67]
	v_lshl_add_u64 v[90:91], s[56:57], 0, v[90:91]
	v_lshl_add_u64 v[90:91], v[90:91], 0, s[0:1]
	v_lshl_add_u64 v[90:91], v[90:91], 0, v[66:67]
	s_waitcnt vmcnt(9)
	v_mov_b32_e32 v60, v16
	v_mov_b32_e32 v61, v18
	v_mov_b32_e32 v18, v17
	s_waitcnt vmcnt(7)
	v_mov_b32_e32 v62, v20
	v_mov_b32_e32 v63, v22
	v_mov_b32_e32 v22, v21
	v_mov_b32_e32 v52, v8
	v_mov_b32_e32 v53, v10
	v_mov_b32_e32 v10, v9
	v_pk_fma_f32 v[8:9], v[60:61], v[94:95], v[62:63]
	v_pk_fma_f32 v[16:17], v[18:19], v[96:97], v[22:23]
	s_waitcnt vmcnt(5)
	v_mov_b32_e32 v94, v36
	v_mov_b32_e32 v95, v38
	v_mov_b32_e32 v38, v37
	s_waitcnt vmcnt(4)
	v_mov_b32_e32 v96, v40
	v_mov_b32_e32 v97, v42
	v_mov_b32_e32 v42, v41
	v_pk_fma_f32 v[8:9], v[94:95], v[116:117], v[8:9]
	v_pk_fma_f32 v[16:17], v[38:39], v[176:177], v[16:17]
	s_waitcnt vmcnt(3)
	v_mov_b32_e32 v98, v44
	v_mov_b32_e32 v99, v46
	v_mov_b32_e32 v46, v45
	v_pk_fma_f32 v[8:9], v[96:97], v[110:111], v[8:9]
	v_pk_fma_f32 v[16:17], v[42:43], v[108:109], v[16:17]
	v_pk_fma_f32 v[8:9], v[98:99], v[56:57], v[8:9]
	v_pk_fma_f32 v[16:17], v[46:47], v[58:59], v[16:17]
	v_mov_b32_e32 v88, v12
	v_mul_f32_e32 v12, 0xbfb8aa3b, v8
	v_mul_f32_e32 v36, 0xbfb8aa3b, v16
	v_mul_f32_e32 v37, 0xbfb8aa3b, v9
	v_pk_mul_f32 v[20:21], v[8:9], s[42:43] op_sel_hi:[1,0]
	v_pk_mul_f32 v[8:9], v[16:17], s[42:43] op_sel_hi:[1,0]
	v_mul_f32_e32 v16, 0xbfb8aa3b, v17
	v_exp_f32_e32 v12, v12
	v_exp_f32_e32 v17, v36
	v_exp_f32_e32 v36, v37
	v_exp_f32_e32 v37, v16
	v_add_f32_e32 v12, 1.0, v12
	v_add_f32_e32 v40, 1.0, v17
	v_add_f32_e32 v17, 1.0, v36
	v_rcp_f32_e32 v16, v12
	v_rcp_f32_e32 v17, v17
	v_mov_b32_e32 v89, v14
	v_add_f32_e32 v12, 1.0, v37
	v_rcp_f32_e32 v36, v40
	v_pk_mul_f32 v[16:17], v[20:21], v[16:17]
	v_pk_fma_f32 v[20:21], v[52:53], v[100:101], v[88:89]
	v_mov_b32_e32 v14, v13
	v_lshlrev_b32_e32 v41, 16, v203
	v_lshlrev_b32_e32 v40, 16, v202
	v_and_b32_e32 v45, 0xffff0000, v203
	v_and_b32_e32 v44, 0xffff0000, v202
	s_waitcnt vmcnt(2)
	v_mov_b32_e32 v54, v28
	v_mov_b32_e32 v55, v30
	v_rcp_f32_e32 v37, v12
	v_pk_fma_f32 v[12:13], v[10:11], v[106:107], v[14:15]
	v_pk_fma_f32 v[20:21], v[54:55], v[112:113], v[20:21]
	v_mov_b32_e32 v30, v29
	s_waitcnt vmcnt(1)
	v_mov_b32_e32 v100, v0
	v_mov_b32_e32 v101, v2
	v_pk_fma_f32 v[12:13], v[30:31], v[114:115], v[12:13]
	v_pk_fma_f32 v[20:21], v[100:101], v[104:105], v[20:21]
	v_mov_b32_e32 v2, v1
	s_waitcnt vmcnt(0)
; __device__ __forceinline__ u32x4 pack8(const float (&v)[8]) { u32x4 o; o.x = pk2(v[0], v[1]); o.y = pk2(v[2], v[3]); o.z = pk2(v[4], v[5]); o.w = pk2(v[6], v[7]); return o; }
; __device__ __forceinline__ void conv4x8(const bf16* proj, int t, int ch, const float* cw, const float* cb, float sc, float (&o)[4][8]) {
;     ...
; #pragma unroll
;     for (int w = 0; w < 4; ++w) {
;         const f32x4 w0 = *(const f32x4*)(cw + w * 1024 + ch), w1 = *(const f32x4*)(cw + w * 1024 + ch + 4);
;         const float wv[8] = {w0[0], w0[1], w0[2], w0[3], w1[0], w1[1], w1[2], w1[3]};
; #pragma unroll
;         for (int j = 0; j < 4; ++j) { float xv[8]; unpack8(raw[j + w], xv);
; #pragma unroll
;             for (int e = 0; e < 8; ++e) o[j][e] += wv[e] * xv[e]; }
;     }
; #pragma unroll
;     for (int j = 0; j < 4; ++j)
; #pragma unroll
;         for (int e = 0; e < 8; ++e) o[j][e] = o[j][e] * sc * __builtin_amdgcn_rcpf(1.0f + __expf(-o[j][e]));
; __device__ __forceinline__ void m1_phase(const Params& p, unsigned char* ldsg, int G) {
;     ...
;         conv4x8(PROJ, t0 + l0, 512 + h * HD + cgp * 8, p.convw, p.convb, 0.08838834764831845f, kk);
; #pragma unroll
;         for (int j = 0; j < 4; ++j) *(u32x4*)(QKC + (size_t)(t0 + l0 + j) * DM + 512 + h * HD + cgp * 8) = pack8(kk[j]);
	v_mov_b32_e32 v106, v32
	v_mov_b32_e32 v107, v34
	v_pk_fma_f32 v[0:1], v[2:3], v[102:103], v[12:13]
	v_pk_fma_f32 v[20:21], v[106:107], v[40:41], v[20:21]
	v_mov_b32_e32 v34, v33
	v_pk_fma_f32 v[0:1], v[34:35], v[44:45], v[0:1]
	v_mul_f32_e32 v12, 0xbfb8aa3b, v20
	v_exp_f32_e32 v28, v12
	v_mul_f32_e32 v12, 0xbfb8aa3b, v0
	v_exp_f32_e32 v29, v12
	v_pk_mul_f32 v[12:13], v[8:9], v[36:37]
	v_add_f32_e32 v8, 1.0, v28
	v_mul_f32_e32 v28, 0xbfb8aa3b, v21
	v_add_f32_e32 v9, 1.0, v29
	v_exp_f32_e32 v29, v28
	v_mul_f32_e32 v28, 0xbfb8aa3b, v1
	v_exp_f32_e32 v32, v28
	v_rcp_f32_e32 v28, v9
	v_add_f32_e32 v9, 1.0, v29
	v_rcp_f32_e32 v8, v8
	v_rcp_f32_e32 v9, v9
	v_add_f32_e32 v29, 1.0, v32
	v_rcp_f32_e32 v29, v29
	v_pk_mul_f32 v[20:21], v[20:21], s[42:43] op_sel_hi:[1,0]
	v_pk_mul_f32 v[0:1], v[0:1], s[42:43] op_sel_hi:[1,0]
	v_pk_mul_f32 v[8:9], v[20:21], v[8:9]
	v_pk_mul_f32 v[0:1], v[0:1], v[28:29]
	v_bfe_u32 v36, v8, 16, 1
	v_bfe_u32 v37, v9, 16, 1
	v_bfe_u32 v20, v1, 16, 1
	v_bfe_u32 v21, v0, 16, 1
	v_add3_u32 v37, v9, v37, s81
	v_add3_u32 v36, v8, v36, s81
	v_add3_u32 v21, v0, v21, s81
	v_add3_u32 v20, v1, v20, s81
	v_bfe_u32 v32, v16, 16, 1
	v_bfe_u32 v33, v17, 16, 1
	v_lshrrev_b32_e32 v36, 16, v36
	v_lshrrev_b32_e32 v37, 16, v37
	v_bfe_u32 v28, v13, 16, 1
	v_bfe_u32 v29, v12, 16, 1
	v_add3_u32 v33, v17, v33, s81
	v_add3_u32 v32, v16, v32, s81
	v_and_or_b32 v151, v20, s64, v37
	v_and_or_b32 v150, v21, s64, v36
	v_lshl_add_u64 v[20:21], s[56:57], 0, v[82:83]
	v_add3_u32 v29, v12, v29, s81
	v_add3_u32 v28, v13, v28, s81
	v_lshrrev_b32_e32 v32, 16, v32
	v_lshrrev_b32_e32 v33, 16, v33
	v_lshl_add_u64 v[20:21], v[20:21], 0, s[0:1]
	v_and_or_b32 v149, v28, s64, v33
	v_and_or_b32 v148, v29, s64, v32
	v_lshl_add_u64 v[20:21], v[20:21], 0, v[66:67]
	v_pk_fma_f32 v[28:29], v[18:19], v[176:177], v[22:23]
	global_store_dwordx4 v[20:21], v[148:151], off offset:1024
	v_pk_fma_f32 v[20:21], v[60:61], v[116:117], v[62:63]
	v_pk_fma_f32 v[28:29], v[38:39], v[108:109], v[28:29]
	v_and_b32_e32 v83, 0xffff0000, v205
	v_and_b32_e32 v82, 0xffff0000, v204
	v_pk_fma_f32 v[20:21], v[94:95], v[110:111], v[20:21]
	v_pk_fma_f32 v[28:29], v[42:43], v[58:59], v[28:29]
	v_lshlrev_b32_e32 v117, 16, v205
	v_lshlrev_b32_e32 v116, 16, v204
	v_pk_fma_f32 v[20:21], v[96:97], v[56:57], v[20:21]
	v_pk_fma_f32 v[28:29], v[46:47], v[82:83], v[28:29]
	v_pk_fma_f32 v[20:21], v[98:99], v[116:117], v[20:21]
	v_mul_f32_e32 v33, 0xbfb8aa3b, v28
	v_mul_f32_e32 v32, 0xbfb8aa3b, v20
	v_exp_f32_e32 v33, v33
	v_mul_f32_e32 v36, 0xbfb8aa3b, v21
	v_exp_f32_e32 v32, v32
	v_exp_f32_e32 v37, v36
	v_add_f32_e32 v33, 1.0, v33
	v_rcp_f32_e32 v36, v33
	v_add_f32_e32 v32, 1.0, v32
	v_add_f32_e32 v33, 1.0, v37
	v_mul_f32_e32 v37, 0xbfb8aa3b, v29
	v_rcp_f32_e32 v32, v32
	v_rcp_f32_e32 v33, v33
	v_exp_f32_e32 v37, v37
	v_pk_mul_f32 v[20:21], v[20:21], s[42:43] op_sel_hi:[1,0]
	v_pk_fma_f32 v[48:49], v[10:11], v[114:115], v[14:15]
	v_pk_mul_f32 v[32:33], v[20:21], v[32:33]
	v_pk_mul_f32 v[20:21], v[28:29], s[42:43] op_sel_hi:[1,0]
	v_add_f32_e32 v28, 1.0, v37
	v_rcp_f32_e32 v37, v28
	v_pk_fma_f32 v[28:29], v[52:53], v[112:113], v[88:89]
	v_lshlrev_b32_e32 v113, 16, v207
	v_pk_fma_f32 v[28:29], v[54:55], v[104:105], v[28:29]
	v_lshlrev_b32_e32 v112, 16, v206
	v_pk_fma_f32 v[48:49], v[30:31], v[102:103], v[48:49]
	v_pk_fma_f32 v[28:29], v[100:101], v[40:41], v[28:29]
	v_and_b32_e32 v115, 0xffff0000, v207
	v_and_b32_e32 v114, 0xffff0000, v206
	v_pk_fma_f32 v[48:49], v[2:3], v[44:45], v[48:49]
	v_pk_fma_f32 v[28:29], v[106:107], v[112:113], v[28:29]
	v_pk_fma_f32 v[48:49], v[34:35], v[114:115], v[48:49]
	v_mul_f32_e32 v50, 0xbfb8aa3b, v28
	v_exp_f32_e32 v50, v50
	v_mul_f32_e32 v51, 0xbfb8aa3b, v48
	v_exp_f32_e32 v51, v51
	v_pk_mul_f32 v[36:37], v[20:21], v[36:37]
	v_add_f32_e32 v20, 1.0, v50
	v_mul_f32_e32 v50, 0xbfb8aa3b, v29
	v_add_f32_e32 v21, 1.0, v51
	v_exp_f32_e32 v51, v50
	v_mul_f32_e32 v50, 0xbfb8aa3b, v49
	v_exp_f32_e32 v75, v50
	v_rcp_f32_e32 v50, v21
	v_add_f32_e32 v21, 1.0, v51
	v_rcp_f32_e32 v20, v20
	v_rcp_f32_e32 v21, v21
	v_add_f32_e32 v51, 1.0, v75
	v_rcp_f32_e32 v51, v51
	v_pk_mul_f32 v[28:29], v[28:29], s[42:43] op_sel_hi:[1,0]
	v_and_b32_e32 v149, 0xffff0000, v209
	v_pk_mul_f32 v[28:29], v[28:29], v[20:21]
	v_pk_mul_f32 v[20:21], v[48:49], s[42:43] op_sel_hi:[1,0]
	v_bfe_u32 v79, v28, 16, 1
	v_pk_mul_f32 v[20:21], v[20:21], v[50:51]
	v_bfe_u32 v50, v37, 16, 1
	v_bfe_u32 v51, v36, 16, 1
	v_add3_u32 v75, v36, v51, s81
	v_add3_u32 v77, v37, v50, s81
	v_bfe_u32 v50, v32, 16, 1
	v_bfe_u32 v51, v33, 16, 1
	v_bfe_u32 v81, v29, 16, 1
	v_bfe_u32 v48, v21, 16, 1
	v_bfe_u32 v49, v20, 16, 1
	v_add3_u32 v81, v29, v81, s81
	v_add3_u32 v79, v28, v79, s81
	v_add3_u32 v51, v33, v51, s81
	v_add3_u32 v50, v32, v50, s81
	v_add3_u32 v49, v20, v49, s81
	v_add3_u32 v48, v21, v48, s81
	v_lshrrev_b32_e32 v147, 16, v50
	v_lshrrev_b32_e32 v148, 16, v51
	v_lshrrev_b32_e32 v50, 16, v79
	v_lshrrev_b32_e32 v51, 16, v81
	v_and_or_b32 v51, v48, s64, v51
	v_and_or_b32 v50, v49, s64, v50
	v_and_or_b32 v49, v77, s64, v148
	v_and_or_b32 v48, v75, s64, v147
	global_store_dwordx4 v[84:85], v[48:51], off offset:1024
	v_lshlrev_b32_e32 v85, 16, v209
	v_lshlrev_b32_e32 v84, 16, v208
	v_and_b32_e32 v148, 0xffff0000, v208
	v_pk_fma_f32 v[24:25], v[60:61], v[110:111], v[62:63]
	v_pk_fma_f32 v[48:49], v[18:19], v[108:109], v[22:23]
	v_pk_fma_f32 v[24:25], v[94:95], v[56:57], v[24:25]
	v_pk_fma_f32 v[48:49], v[38:39], v[58:59], v[48:49]
	v_pk_fma_f32 v[24:25], v[96:97], v[116:117], v[24:25]
	v_pk_fma_f32 v[48:49], v[42:43], v[82:83], v[48:49]
	v_pk_fma_f32 v[24:25], v[98:99], v[84:85], v[24:25]
	v_lshlrev_b32_e32 v111, 16, v211
; __device__ __forceinline__ u32x4 pack8(const float (&v)[8]) { u32x4 o; o.x = pk2(v[0], v[1]); o.y = pk2(v[2], v[3]); o.z = pk2(v[4], v[5]); o.w = pk2(v[6], v[7]); return o; }
; __device__ __forceinline__ void conv4x8(const bf16* proj, int t, int ch, const float* cw, const float* cb, float sc, float (&o)[4][8]) {
;     ...
; #pragma unroll
;     for (int w = 0; w < 4; ++w) {
;         const f32x4 w0 = *(const f32x4*)(cw + w * 1024 + ch), w1 = *(const f32x4*)(cw + w * 1024 + ch + 4);
;         const float wv[8] = {w0[0], w0[1], w0[2], w0[3], w1[0], w1[1], w1[2], w1[3]};
; #pragma unroll
;         for (int j = 0; j < 4; ++j) { float xv[8]; unpack8(raw[j + w], xv);
; #pragma unroll
;             for (int e = 0; e < 8; ++e) o[j][e] += wv[e] * xv[e]; }
;     }
; #pragma unroll
;     for (int j = 0; j < 4; ++j)
; #pragma unroll
;         for (int e = 0; e < 8; ++e) o[j][e] = o[j][e] * sc * __builtin_amdgcn_rcpf(1.0f + __expf(-o[j][e]));
; __device__ __forceinline__ void m1_phase(const Params& p, unsigned char* ldsg, int G) {
;     ...
;         conv4x8(PROJ, t0 + l0, 512 + h * HD + cgp * 8, p.convw, p.convb, 0.08838834764831845f, kk);
; #pragma unroll
;         for (int j = 0; j < 4; ++j) *(u32x4*)(QKC + (size_t)(t0 + l0 + j) * DM + 512 + h * HD + cgp * 8) = pack8(kk[j]);
	v_mul_f32_e32 v50, 0xbfb8aa3b, v24
	v_exp_f32_e32 v75, v50
	v_pk_fma_f32 v[50:51], v[46:47], v[148:149], v[48:49]
	v_lshlrev_b32_e32 v110, 16, v210
	v_mul_f32_e32 v49, 0xbfb8aa3b, v50
	v_add_f32_e32 v48, 1.0, v75
	v_exp_f32_e32 v49, v49
	v_mul_f32_e32 v75, 0xbfb8aa3b, v25
	v_exp_f32_e32 v75, v75
	v_rcp_f32_e32 v48, v48
	v_add_f32_e32 v49, 1.0, v49
	v_rcp_f32_e32 v108, v49
	v_add_f32_e32 v49, 1.0, v75
	v_mul_f32_e32 v75, 0xbfb8aa3b, v51
	v_rcp_f32_e32 v49, v49
	v_exp_f32_e32 v75, v75
	v_pk_mul_f32 v[24:25], v[24:25], s[42:43] op_sel_hi:[1,0]
	v_and_b32_e32 v151, 0xffff0000, v211
	v_pk_mul_f32 v[48:49], v[24:25], v[48:49]
	v_pk_mul_f32 v[24:25], v[50:51], s[42:43] op_sel_hi:[1,0]
	v_add_f32_e32 v50, 1.0, v75
	v_and_b32_e32 v150, 0xffff0000, v210
	v_pk_fma_f32 v[26:27], v[52:53], v[104:105], v[88:89]
	v_rcp_f32_e32 v109, v50
	v_pk_fma_f32 v[50:51], v[10:11], v[102:103], v[14:15]
	v_pk_fma_f32 v[26:27], v[54:55], v[40:41], v[26:27]
	v_pk_fma_f32 v[50:51], v[30:31], v[44:45], v[50:51]
	v_pk_fma_f32 v[26:27], v[100:101], v[112:113], v[26:27]
	v_pk_fma_f32 v[50:51], v[2:3], v[114:115], v[50:51]
	v_pk_fma_f32 v[26:27], v[106:107], v[110:111], v[26:27]
	v_pk_fma_f32 v[102:103], v[34:35], v[150:151], v[50:51]
	v_mul_f32_e32 v50, 0xbfb8aa3b, v26
	v_exp_f32_e32 v75, v50
	v_mul_f32_e32 v50, 0xbfb8aa3b, v102
	v_exp_f32_e32 v77, v50
	v_pk_mul_f32 v[50:51], v[24:25], v[108:109]
	v_add_f32_e32 v24, 1.0, v75
	v_mul_f32_e32 v75, 0xbfb8aa3b, v27
	v_add_f32_e32 v25, 1.0, v77
	v_exp_f32_e32 v75, v75
	v_mul_f32_e32 v77, 0xbfb8aa3b, v103
	v_exp_f32_e32 v77, v77
	v_rcp_f32_e32 v104, v25
	v_add_f32_e32 v25, 1.0, v75
	v_rcp_f32_e32 v24, v24
	v_rcp_f32_e32 v25, v25
	v_add_f32_e32 v75, 1.0, v77
	v_rcp_f32_e32 v105, v75
	v_pk_mul_f32 v[26:27], v[26:27], s[42:43] op_sel_hi:[1,0]
	v_bfe_u32 v79, v51, 16, 1
	v_pk_mul_f32 v[26:27], v[26:27], v[24:25]
	v_pk_mul_f32 v[24:25], v[102:103], s[42:43] op_sel_hi:[1,0]
	v_bfe_u32 v102, v48, 16, 1
	v_pk_mul_f32 v[24:25], v[24:25], v[104:105]
	v_bfe_u32 v103, v49, 16, 1
	v_bfe_u32 v104, v26, 16, 1
	v_bfe_u32 v105, v27, 16, 1
	v_bfe_u32 v75, v25, 16, 1
	v_bfe_u32 v77, v24, 16, 1
	v_bfe_u32 v81, v50, 16, 1
	v_add3_u32 v105, v27, v105, s81
	v_add3_u32 v104, v26, v104, s81
	v_add3_u32 v103, v49, v103, s81
	v_add3_u32 v102, v48, v102, s81
	v_add3_u32 v81, v50, v81, s81
	v_add3_u32 v79, v51, v79, s81
	v_add3_u32 v77, v24, v77, s81
	v_add3_u32 v75, v25, v75, s81
	v_lshrrev_b32_e32 v102, 16, v102
	v_lshrrev_b32_e32 v103, 16, v103
	v_lshrrev_b32_e32 v104, 16, v104
	v_lshrrev_b32_e32 v105, 16, v105
	v_pk_fma_f32 v[18:19], v[18:19], v[58:59], v[22:23]
	v_and_or_b32 v105, v75, s64, v105
	v_and_or_b32 v104, v77, s64, v104
	v_and_or_b32 v103, v79, s64, v103
	v_and_or_b32 v102, v81, s64, v102
	v_pk_fma_f32 v[56:57], v[60:61], v[56:57], v[62:63]
	v_pk_fma_f32 v[18:19], v[38:39], v[82:83], v[18:19]
	global_store_dwordx4 v[90:91], v[102:105], off offset:1024
	v_lshlrev_b32_e32 v91, 16, v213
	v_lshlrev_b32_e32 v90, 16, v212
	v_and_b32_e32 v5, 0xffff0000, v213
	v_and_b32_e32 v4, 0xffff0000, v212
	v_pk_fma_f32 v[22:23], v[94:95], v[116:117], v[56:57]
	v_pk_fma_f32 v[18:19], v[42:43], v[148:149], v[18:19]
	v_pk_fma_f32 v[22:23], v[96:97], v[84:85], v[22:23]
	v_pk_fma_f32 v[4:5], v[46:47], v[4:5], v[18:19]
	v_pk_fma_f32 v[22:23], v[98:99], v[90:91], v[22:23]
	v_mul_f32_e32 v19, 0xbfb8aa3b, v4
	v_mul_f32_e32 v56, 0xbfb8aa3b, v22
	v_exp_f32_e32 v19, v19
	v_mul_f32_e32 v38, 0xbfb8aa3b, v23
	v_exp_f32_e32 v56, v56
	v_exp_f32_e32 v39, v38
	v_add_f32_e32 v19, 1.0, v19
	v_rcp_f32_e32 v38, v19
	v_add_f32_e32 v18, 1.0, v56
	v_add_f32_e32 v19, 1.0, v39
	v_mul_f32_e32 v39, 0xbfb8aa3b, v5
	v_rcp_f32_e32 v18, v18
	v_rcp_f32_e32 v19, v19
	v_exp_f32_e32 v39, v39
	v_pk_mul_f32 v[22:23], v[22:23], s[42:43] op_sel_hi:[1,0]
	v_pk_fma_f32 v[40:41], v[52:53], v[40:41], v[88:89]
	v_pk_mul_f32 v[18:19], v[22:23], v[18:19]
	v_add_f32_e32 v22, 1.0, v39
	v_pk_fma_f32 v[10:11], v[10:11], v[44:45], v[14:15]
	v_pk_fma_f32 v[14:15], v[54:55], v[112:113], v[40:41]
	v_rcp_f32_e32 v39, v22
	v_lshlrev_b32_e32 v23, 16, v215
	v_lshlrev_b32_e32 v22, 16, v214
	v_pk_fma_f32 v[10:11], v[30:31], v[114:115], v[10:11]
	v_pk_fma_f32 v[14:15], v[100:101], v[110:111], v[14:15]
	v_and_b32_e32 v7, 0xffff0000, v215
	v_and_b32_e32 v6, 0xffff0000, v214
	v_pk_fma_f32 v[2:3], v[2:3], v[150:151], v[10:11]
	v_pk_fma_f32 v[10:11], v[106:107], v[22:23], v[14:15]
	v_pk_fma_f32 v[2:3], v[34:35], v[6:7], v[2:3]
	v_mul_f32_e32 v6, 0xbfb8aa3b, v10
	v_exp_f32_e32 v6, v6
	v_mul_f32_e32 v7, 0xbfb8aa3b, v2
	v_exp_f32_e32 v7, v7
	v_pk_mul_f32 v[4:5], v[4:5], s[42:43] op_sel_hi:[1,0]
	s_nop 0
	v_pk_mul_f32 v[14:15], v[4:5], v[38:39]
	v_add_f32_e32 v4, 1.0, v6
	v_mul_f32_e32 v6, 0xbfb8aa3b, v11
	v_add_f32_e32 v5, 1.0, v7
	v_exp_f32_e32 v7, v6
	v_mul_f32_e32 v6, 0xbfb8aa3b, v3
	v_exp_f32_e32 v22, v6
	v_rcp_f32_e32 v6, v5
	v_add_f32_e32 v5, 1.0, v7
	v_rcp_f32_e32 v4, v4
	v_add_f32_e32 v7, 1.0, v22
	v_rcp_f32_e32 v5, v5
	v_rcp_f32_e32 v7, v7
	v_pk_mul_f32 v[10:11], v[10:11], s[42:43] op_sel_hi:[1,0]
	v_pk_mul_f32 v[2:3], v[2:3], s[42:43] op_sel_hi:[1,0]
	v_pk_mul_f32 v[10:11], v[10:11], v[4:5]
	v_pk_mul_f32 v[2:3], v[2:3], v[6:7]
	v_bfe_u32 v6, v15, 16, 1
	v_bfe_u32 v7, v14, 16, 1
	v_add3_u32 v22, v14, v7, s81
	v_add3_u32 v23, v15, v6, s81
	v_bfe_u32 v6, v18, 16, 1
	v_bfe_u32 v7, v19, 16, 1
	v_bfe_u32 v30, v10, 16, 1
	v_bfe_u32 v31, v11, 16, 1
	v_bfe_u32 v4, v3, 16, 1
	v_bfe_u32 v5, v2, 16, 1
	v_add3_u32 v31, v11, v31, s81
	v_add3_u32 v30, v10, v30, s81
	v_add3_u32 v7, v19, v7, s81
	v_add3_u32 v6, v18, v6, s81
	v_add3_u32 v5, v2, v5, s81
	v_add3_u32 v4, v3, v4, s81
	v_lshrrev_b32_e32 v34, 16, v6
	v_lshrrev_b32_e32 v35, 16, v7
; __device__ __forceinline__ unsigned pk2(float lo, float hi) { return f2bf(lo) | (f2bf(hi) << 16); }
; __device__ __forceinline__ u32x4 pack8(const float (&v)[8]) { u32x4 o; o.x = pk2(v[0], v[1]); o.y = pk2(v[2], v[3]); o.z = pk2(v[4], v[5]); o.w = pk2(v[6], v[7]); return o; }
; __device__ __forceinline__ void m1_phase(const Params& p, unsigned char* ldsg, int G) {
;     ...
;         for (int j = 0; j < 4; ++j) *(u32x4*)(QKC + (size_t)(t0 + l0 + j) * DM + 512 + h * HD + cgp * 8) = pack8(kk[j]);
;         {
;             u32x4 rv[4];
; #pragma unroll
;             for (int j = 0; j < 4; ++j) rv[j] = *(const u32x4*)(PROJ + (size_t)(t0 + l0 + j) * NPROJ + 1024 + h * HD + cgp * 8);
; #pragma unroll
;             for (int e = 0; e < 8; ++e) {
;                 const unsigned sh = (e & 1) * 16;
;                 u32x2 o; o.x = ((rv[0][e >> 1] >> sh) & 0xffffu) | (((rv[1][e >> 1] >> sh) & 0xffffu) << 16); o.y = ((rv[2][e >> 1] >> sh) & 0xffffu) | (((rv[3][e >> 1] >> sh) & 0xffffu) << 16);
;                 *(u32x2*)(VT + tsw(cgp * 8 + e, l0)) = o;
;             }
;         }
;         __syncthreads();
;         {
;             const f32x4 w4 = *(const f32x4*)(sW + l0);
; #pragma unroll
;             for (int e = 0; e < 8; ++e) { u32x2 o; o.x = pk2(kk[0][e] * w4[0], kk[1][e] * w4[1]); o.y = pk2(kk[2][e] * w4[2], kk[3][e] * w4[3]); *(u32x2*)(KT + tsw(cgp * 8 + e, l0)) = o; }
	v_lshrrev_b32_e32 v6, 16, v30
	v_lshrrev_b32_e32 v7, 16, v31
	v_and_or_b32 v7, v4, s64, v7
	v_and_or_b32 v6, v5, s64, v6
	v_and_or_b32 v5, v23, s64, v35
	v_and_or_b32 v4, v22, s64, v34
	v_lshl_add_u64 v[22:23], s[56:57], 0, v[86:87]
	v_lshl_add_u64 v[22:23], v[22:23], 0, s[0:1]
	v_lshl_add_u64 v[22:23], v[22:23], 0, v[66:67]
	global_store_dwordx4 v[22:23], v[4:7], off offset:1024
	v_add_u32_e32 v34, 0x4800, v142
	v_mov_b32_e32 v35, v18
	s_lshl_b32 s0, s44, 14
	s_add_i32 s0, s0, s83
	v_and_b32_e32 v22, 0xffff, v216
	v_lshrrev_b32_e32 v4, 16, v216
	v_and_or_b32 v30, v220, s64, v4
	v_lshl_or_b32 v22, v220, 16, v22
	v_add_u32_e32 v38, s0, v127
	v_and_b32_e32 v23, 0xffff, v224
	v_lshrrev_b32_e32 v4, 16, v224
	v_lshl_or_b32 v23, v250, 16, v23
	v_and_or_b32 v31, v250, s64, v4
	v_and_b32_e32 v4, 0xffff, v217
	ds_write2_b64 v34, v[22:23], v[30:31] offset1:18
	v_lshl_or_b32 v22, v221, 16, v4
	v_and_b32_e32 v4, 0xffff, v225
	v_lshl_or_b32 v23, v251, 16, v4
	v_lshrrev_b32_e32 v4, 16, v217
	v_lshrrev_b32_e32 v5, 16, v225
	v_and_or_b32 v4, v221, s64, v4
	v_and_or_b32 v5, v251, s64, v5
	ds_write2_b64 v34, v[22:23], v[4:5] offset0:36 offset1:54
	v_and_b32_e32 v4, 0xffff, v218
	v_lshrrev_b32_e32 v6, 16, v218
	v_and_b32_e32 v5, 0xffff, v226
	v_and_or_b32 v22, v222, s64, v6
	v_lshrrev_b32_e32 v6, 16, v226
	v_lshl_or_b32 v4, v222, 16, v4
	v_lshl_or_b32 v5, v252, 16, v5
	v_and_or_b32 v23, v252, s64, v6
	ds_write2_b64 v34, v[4:5], v[22:23] offset0:72 offset1:90
	v_and_b32_e32 v4, 0xffff, v219
	v_and_b32_e32 v5, 0xffff, v227
	v_lshrrev_b32_e32 v6, 16, v219
	v_lshrrev_b32_e32 v7, 16, v227
	v_lshl_or_b32 v4, v223, 16, v4
	v_lshl_or_b32 v5, v253, 16, v5
	v_and_or_b32 v6, v223, s64, v6
	v_and_or_b32 v7, v253, s64, v7
	ds_write2_b64 v34, v[4:5], v[6:7] offset0:108 offset1:126
	s_waitcnt lgkmcnt(0)
	s_barrier
	ds_read_b128 v[4:7], v120 offset:36864
	v_mov_b32_e32 v22, v16
	v_mov_b32_e32 v23, v48
	v_mov_b32_e32 v34, v32
	v_mov_b32_e32 v48, v17
	s_waitcnt lgkmcnt(0)
	v_mov_b32_e32 v30, v4
	v_mov_b32_e32 v31, v6
	v_pk_mul_f32 v[22:23], v[22:23], v[30:31]
	v_mov_b32_e32 v6, v5
	v_pk_mul_f32 v[4:5], v[34:35], v[6:7]
	v_and_b32_sdwa v16, v23, v146 dst_sel:DWORD dst_unused:UNUSED_PAD src0_sel:WORD_1 src1_sel:DWORD
	v_and_b32_sdwa v18, v22, v146 dst_sel:DWORD dst_unused:UNUSED_PAD src0_sel:WORD_1 src1_sel:DWORD
	v_add3_u32 v18, v22, v18, s81
	v_add3_u32 v16, v23, v16, s81
	v_and_b32_sdwa v22, v5, v146 dst_sel:DWORD dst_unused:UNUSED_PAD src0_sel:WORD_1 src1_sel:DWORD
	v_and_b32_sdwa v23, v4, v146 dst_sel:DWORD dst_unused:UNUSED_PAD src0_sel:WORD_1 src1_sel:DWORD
	v_add3_u32 v5, v5, v22, s81
	v_add3_u32 v4, v4, v23, s81
	v_mov_b32_e32 v34, v36
	v_mov_b32_e32 v35, v14
	v_and_b32_e32 v5, 0xffff0000, v5
	v_and_b32_e32 v4, 0xffff0000, v4
	v_mov_b32_e32 v22, v12
	v_mov_b32_e32 v23, v50
	v_pk_mul_f32 v[34:35], v[34:35], v[6:7]
	v_or_b32_sdwa v5, v5, v16 dst_sel:DWORD dst_unused:UNUSED_PAD src0_sel:DWORD src1_sel:WORD_1
	v_or_b32_sdwa v4, v4, v18 dst_sel:DWORD dst_unused:UNUSED_PAD src0_sel:DWORD src1_sel:WORD_1
	v_pk_mul_f32 v[22:23], v[22:23], v[30:31]
	v_and_b32_sdwa v16, v35, v146 dst_sel:DWORD dst_unused:UNUSED_PAD src0_sel:WORD_1 src1_sel:DWORD
	v_and_b32_sdwa v18, v34, v146 dst_sel:DWORD dst_unused:UNUSED_PAD src0_sel:WORD_1 src1_sel:DWORD
	v_and_b32_sdwa v12, v23, v146 dst_sel:DWORD dst_unused:UNUSED_PAD src0_sel:WORD_1 src1_sel:DWORD
	v_and_b32_sdwa v14, v22, v146 dst_sel:DWORD dst_unused:UNUSED_PAD src0_sel:WORD_1 src1_sel:DWORD
	v_add3_u32 v16, v35, v16, s81
	v_add3_u32 v18, v34, v18, s81
	v_add3_u32 v14, v22, v14, s81
	v_add3_u32 v12, v23, v12, s81
	v_and_b32_e32 v16, 0xffff0000, v16
	v_and_b32_e32 v18, 0xffff0000, v18
	v_or_b32_sdwa v23, v16, v12 dst_sel:DWORD dst_unused:UNUSED_PAD src0_sel:DWORD src1_sel:WORD_1
	v_or_b32_sdwa v22, v18, v14 dst_sel:DWORD dst_unused:UNUSED_PAD src0_sel:DWORD src1_sel:WORD_1
	ds_write2_b64 v142, v[4:5], v[22:23] offset1:18
	v_pk_mul_f32 v[4:5], v[48:49], v[30:31]
	v_mov_b32_e32 v18, v33
	v_pk_mul_f32 v[16:17], v[18:19], v[6:7]
	v_and_b32_sdwa v12, v5, v146 dst_sel:DWORD dst_unused:UNUSED_PAD src0_sel:WORD_1 src1_sel:DWORD
	v_and_b32_sdwa v14, v4, v146 dst_sel:DWORD dst_unused:UNUSED_PAD src0_sel:WORD_1 src1_sel:DWORD
	v_add3_u32 v4, v4, v14, s81
	v_add3_u32 v5, v5, v12, s81
	v_and_b32_sdwa v12, v17, v146 dst_sel:DWORD dst_unused:UNUSED_PAD src0_sel:WORD_1 src1_sel:DWORD
	v_and_b32_sdwa v14, v16, v146 dst_sel:DWORD dst_unused:UNUSED_PAD src0_sel:WORD_1 src1_sel:DWORD
	v_add3_u32 v12, v17, v12, s81
	v_add3_u32 v14, v16, v14, s81
	v_and_b32_e32 v12, 0xffff0000, v12
	v_and_b32_e32 v14, 0xffff0000, v14
	v_mov_b32_e32 v50, v13
	v_or_b32_sdwa v5, v12, v5 dst_sel:DWORD dst_unused:UNUSED_PAD src0_sel:DWORD src1_sel:WORD_1
	v_or_b32_sdwa v4, v14, v4 dst_sel:DWORD dst_unused:UNUSED_PAD src0_sel:DWORD src1_sel:WORD_1
	v_pk_mul_f32 v[12:13], v[50:51], v[30:31]
	v_mov_b32_e32 v14, v37
	v_pk_mul_f32 v[14:15], v[14:15], v[6:7]
	v_and_b32_sdwa v16, v13, v146 dst_sel:DWORD dst_unused:UNUSED_PAD src0_sel:WORD_1 src1_sel:DWORD
	v_and_b32_sdwa v17, v12, v146 dst_sel:DWORD dst_unused:UNUSED_PAD src0_sel:WORD_1 src1_sel:DWORD
	v_add3_u32 v12, v12, v17, s81
	v_add3_u32 v13, v13, v16, s81
	v_and_b32_sdwa v16, v15, v146 dst_sel:DWORD dst_unused:UNUSED_PAD src0_sel:WORD_1 src1_sel:DWORD
	v_and_b32_sdwa v17, v14, v146 dst_sel:DWORD dst_unused:UNUSED_PAD src0_sel:WORD_1 src1_sel:DWORD
	v_add3_u32 v15, v15, v16, s81
	v_add3_u32 v14, v14, v17, s81
	v_and_b32_e32 v15, 0xffff0000, v15
	v_and_b32_e32 v14, 0xffff0000, v14
	v_or_b32_sdwa v13, v15, v13 dst_sel:DWORD dst_unused:UNUSED_PAD src0_sel:DWORD src1_sel:WORD_1
	v_or_b32_sdwa v12, v14, v12 dst_sel:DWORD dst_unused:UNUSED_PAD src0_sel:DWORD src1_sel:WORD_1
; __device__ __forceinline__ unsigned pk2(float lo, float hi) { return f2bf(lo) | (f2bf(hi) << 16); }
; __device__ __forceinline__ void m1_phase(const Params& p, unsigned char* ldsg, int G) {
;     ...
;             const f32x4 w4 = *(const f32x4*)(sW + l0);
; #pragma unroll
;             for (int e = 0; e < 8; ++e) { u32x2 o; o.x = pk2(kk[0][e] * w4[0], kk[1][e] * w4[1]); o.y = pk2(kk[2][e] * w4[2], kk[3][e] * w4[3]); *(u32x2*)(KT + tsw(cgp * 8 + e, l0)) = o; }
;         }
;         __syncthreads();
;         {
;             bf16x8 av[2][2];
; #pragma unroll
;             for (int mi = 0; mi < 2; ++mi)
; #pragma unroll
;                 for (int ks = 0; ks < 2; ++ks) av[mi][ks] = *(const bf16x8*)(VT + tsw(16 * (2 * hw + mi) + fr, ks * 32 + fq * 8));
; #pragma unroll
;             for (int nt = 0; nt < 8; ++nt) {
;                 bf16x8 bk[2];
; #pragma unroll
;                 for (int ks = 0; ks < 2; ++ks) bk[ks] = *(const bf16x8*)(KT + tsw(16 * nt + fr, ks * 32 + fq * 8));
; #pragma unroll
;                 for (int mi = 0; mi < 2; ++mi) {
;                     f32x4 acc = (f32x4){0.f, 0.f, 0.f, 0.f};
; #pragma unroll
;                     for (int ks = 0; ks < 2; ++ks) acc = __builtin_amdgcn_mfma_f32_16x16x32_bf16(bk[ks], av[mi][ks], acc, 0, 0, 0);
;                     u32x2 o; o.x = pk2(acc[0], acc[1]); o.y = pk2(acc[2], acc[3]);
;                     { const int vd = 16 * (2 * hw + mi) + fr; *(u32x2*)(DCB + ((size_t)((h * 64 + (vd >> 1)) * NCH + c) << 8) + (vd & 1) * 128 + 16 * nt + fq * 4) = o; }
	ds_write2_b64 v142, v[4:5], v[12:13] offset0:36 offset1:54
	v_mov_b32_e32 v4, v8
	v_mov_b32_e32 v5, v26
	v_pk_mul_f32 v[4:5], v[4:5], v[30:31]
	v_mov_b32_e32 v12, v28
	v_mov_b32_e32 v13, v10
	v_pk_mul_f32 v[12:13], v[12:13], v[6:7]
	v_and_b32_sdwa v8, v5, v146 dst_sel:DWORD dst_unused:UNUSED_PAD src0_sel:WORD_1 src1_sel:DWORD
	v_and_b32_sdwa v10, v4, v146 dst_sel:DWORD dst_unused:UNUSED_PAD src0_sel:WORD_1 src1_sel:DWORD
	v_add3_u32 v4, v4, v10, s81
	v_add3_u32 v5, v5, v8, s81
	v_and_b32_sdwa v8, v13, v146 dst_sel:DWORD dst_unused:UNUSED_PAD src0_sel:WORD_1 src1_sel:DWORD
	v_and_b32_sdwa v10, v12, v146 dst_sel:DWORD dst_unused:UNUSED_PAD src0_sel:WORD_1 src1_sel:DWORD
	v_add3_u32 v8, v13, v8, s81
	v_add3_u32 v10, v12, v10, s81
	v_mov_b32_e32 v14, v20
	v_mov_b32_e32 v15, v2
	v_and_b32_e32 v8, 0xffff0000, v8
	v_and_b32_e32 v10, 0xffff0000, v10
	v_mov_b32_e32 v12, v0
	v_mov_b32_e32 v13, v24
	v_pk_mul_f32 v[14:15], v[14:15], v[6:7]
	v_or_b32_sdwa v5, v8, v5 dst_sel:DWORD dst_unused:UNUSED_PAD src0_sel:DWORD src1_sel:WORD_1
	v_or_b32_sdwa v4, v10, v4 dst_sel:DWORD dst_unused:UNUSED_PAD src0_sel:DWORD src1_sel:WORD_1
	v_pk_mul_f32 v[12:13], v[12:13], v[30:31]
	v_and_b32_sdwa v8, v15, v146 dst_sel:DWORD dst_unused:UNUSED_PAD src0_sel:WORD_1 src1_sel:DWORD
	v_and_b32_sdwa v10, v14, v146 dst_sel:DWORD dst_unused:UNUSED_PAD src0_sel:WORD_1 src1_sel:DWORD
	v_and_b32_sdwa v0, v13, v146 dst_sel:DWORD dst_unused:UNUSED_PAD src0_sel:WORD_1 src1_sel:DWORD
	v_and_b32_sdwa v2, v12, v146 dst_sel:DWORD dst_unused:UNUSED_PAD src0_sel:WORD_1 src1_sel:DWORD
	v_add3_u32 v8, v15, v8, s81
	v_add3_u32 v10, v14, v10, s81
	v_add3_u32 v2, v12, v2, s81
	v_add3_u32 v0, v13, v0, s81
	v_and_b32_e32 v8, 0xffff0000, v8
	v_and_b32_e32 v10, 0xffff0000, v10
	v_or_b32_sdwa v13, v8, v0 dst_sel:DWORD dst_unused:UNUSED_PAD src0_sel:DWORD src1_sel:WORD_1
	v_or_b32_sdwa v12, v10, v2 dst_sel:DWORD dst_unused:UNUSED_PAD src0_sel:DWORD src1_sel:WORD_1
	v_mov_b32_e32 v26, v9
	ds_write2_b64 v142, v[4:5], v[12:13] offset0:72 offset1:90
	v_pk_mul_f32 v[4:5], v[26:27], v[30:31]
	v_mov_b32_e32 v10, v29
	v_pk_mul_f32 v[8:9], v[10:11], v[6:7]
	v_and_b32_sdwa v0, v5, v146 dst_sel:DWORD dst_unused:UNUSED_PAD src0_sel:WORD_1 src1_sel:DWORD
	v_and_b32_sdwa v2, v4, v146 dst_sel:DWORD dst_unused:UNUSED_PAD src0_sel:WORD_1 src1_sel:DWORD
	v_add3_u32 v2, v4, v2, s81
	v_add3_u32 v0, v5, v0, s81
	v_and_b32_sdwa v4, v9, v146 dst_sel:DWORD dst_unused:UNUSED_PAD src0_sel:WORD_1 src1_sel:DWORD
	v_and_b32_sdwa v5, v8, v146 dst_sel:DWORD dst_unused:UNUSED_PAD src0_sel:WORD_1 src1_sel:DWORD
	v_add3_u32 v4, v9, v4, s81
	v_add3_u32 v5, v8, v5, s81
	v_and_b32_e32 v4, 0xffff0000, v4
	v_and_b32_e32 v8, 0xffff0000, v5
	v_mov_b32_e32 v24, v1
	v_or_b32_sdwa v5, v4, v0 dst_sel:DWORD dst_unused:UNUSED_PAD src0_sel:DWORD src1_sel:WORD_1
	v_or_b32_sdwa v4, v8, v2 dst_sel:DWORD dst_unused:UNUSED_PAD src0_sel:DWORD src1_sel:WORD_1
	v_pk_mul_f32 v[0:1], v[24:25], v[30:31]
	v_mov_b32_e32 v2, v21
	v_pk_mul_f32 v[2:3], v[2:3], v[6:7]
	v_and_b32_sdwa v6, v1, v146 dst_sel:DWORD dst_unused:UNUSED_PAD src0_sel:WORD_1 src1_sel:DWORD
	v_and_b32_sdwa v7, v0, v146 dst_sel:DWORD dst_unused:UNUSED_PAD src0_sel:WORD_1 src1_sel:DWORD
	v_add3_u32 v0, v0, v7, s81
	v_add3_u32 v1, v1, v6, s81
	v_and_b32_sdwa v6, v3, v146 dst_sel:DWORD dst_unused:UNUSED_PAD src0_sel:WORD_1 src1_sel:DWORD
	v_and_b32_sdwa v7, v2, v146 dst_sel:DWORD dst_unused:UNUSED_PAD src0_sel:WORD_1 src1_sel:DWORD
	v_add3_u32 v3, v3, v6, s81
	v_add3_u32 v2, v2, v7, s81
	v_and_b32_e32 v3, 0xffff0000, v3
	v_and_b32_e32 v2, 0xffff0000, v2
	v_or_b32_sdwa v1, v3, v1 dst_sel:DWORD dst_unused:UNUSED_PAD src0_sel:DWORD src1_sel:WORD_1
	v_or_b32_sdwa v0, v2, v0 dst_sel:DWORD dst_unused:UNUSED_PAD src0_sel:DWORD src1_sel:WORD_1
	ds_write2_b64 v142, v[4:5], v[0:1] offset0:108 offset1:126
	s_waitcnt lgkmcnt(0)
	s_barrier
	ds_read_b128 v[16:19], v125
	ds_read_b128 v[20:23], v126
	ds_read_b128 v[12:15], v121 offset:18432
	ds_read_b128 v[8:11], v122 offset:18432
	ds_read_b128 v[4:7], v123 offset:18432
	ds_read_b128 v[0:3], v124 offset:18432
	ds_read_b128 v[24:27], v125 offset:9216
	s_waitcnt lgkmcnt(4)
	v_mfma_f32_16x16x32_bf16 v[28:31], v[16:19], v[12:15], 0
	ds_read_b128 v[32:35], v126 offset:9216
	v_ashrrev_i32_e32 v39, 31, v38
	s_waitcnt lgkmcnt(4)
	v_mfma_f32_16x16x32_bf16 v[28:31], v[20:23], v[8:11], v[28:31]
	s_nop 7
	v_bfe_u32 v36, v28, 16, 1
	v_add3_u32 v28, v28, v36, s81
	v_bfe_u32 v36, v29, 16, 1
	v_lshrrev_b32_e32 v28, 16, v28
	v_add3_u32 v29, v29, v36, s81
	v_and_or_b32 v36, v29, s64, v28
	v_bfe_u32 v28, v30, 16, 1
	v_add3_u32 v28, v30, v28, s81
	v_bfe_u32 v29, v31, 16, 1
	v_lshrrev_b32_e32 v28, 16, v28
	v_add3_u32 v29, v31, v29, s81
	v_and_or_b32 v37, v29, s64, v28
	s_waitcnt lgkmcnt(3)
	v_mfma_f32_16x16x32_bf16 v[28:31], v[16:19], v[4:7], 0
	v_lshlrev_b64 v[16:17], 9, v[38:39]
	v_lshl_add_u64 v[16:17], v[70:71], 0, v[16:17]
	global_store_dwordx2 v[16:17], v[36:37], off
	s_waitcnt lgkmcnt(2)
	v_mfma_f32_16x16x32_bf16 v[18:21], v[20:23], v[0:3], v[28:31]
	ds_read_b128 v[36:39], v130
	s_nop 1
	ds_read_b128 v[28:31], v129
	s_nop 3
	v_bfe_u32 v22, v18, 16, 1
	v_add3_u32 v18, v18, v22, s81
	v_bfe_u32 v22, v19, 16, 1
	v_lshrrev_b32_e32 v18, 16, v18
	v_add3_u32 v19, v19, v22, s81
	v_and_or_b32 v40, v19, s64, v18
	v_bfe_u32 v18, v20, 16, 1
	v_bfe_u32 v19, v21, 16, 1
	v_add3_u32 v18, v20, v18, s81
	v_add3_u32 v19, v21, v19, s81
	s_waitcnt lgkmcnt(0)
; __device__ __forceinline__ unsigned pk2(float lo, float hi) { return f2bf(lo) | (f2bf(hi) << 16); }
; __device__ __forceinline__ void m1_phase(const Params& p, unsigned char* ldsg, int G) {
;     ...
;                 for (int ks = 0; ks < 2; ++ks) av[mi][ks] = *(const bf16x8*)(VT + tsw(16 * (2 * hw + mi) + fr, ks * 32 + fq * 8));
; #pragma unroll
;             for (int nt = 0; nt < 8; ++nt) {
;                 bf16x8 bk[2];
; #pragma unroll
;                 for (int ks = 0; ks < 2; ++ks) bk[ks] = *(const bf16x8*)(KT + tsw(16 * nt + fr, ks * 32 + fq * 8));
; #pragma unroll
;                 for (int mi = 0; mi < 2; ++mi) {
;                     f32x4 acc = (f32x4){0.f, 0.f, 0.f, 0.f};
; #pragma unroll
;                     for (int ks = 0; ks < 2; ++ks) acc = __builtin_amdgcn_mfma_f32_16x16x32_bf16(bk[ks], av[mi][ks], acc, 0, 0, 0);
;                     u32x2 o; o.x = pk2(acc[0], acc[1]); o.y = pk2(acc[2], acc[3]);
;                     { const int vd = 16 * (2 * hw + mi) + fr; *(u32x2*)(DCB + ((size_t)((h * 64 + (vd >> 1)) * NCH + c) << 8) + (vd & 1) * 128 + 16 * nt + fq * 4) = o; }
;                 }
	v_mfma_f32_16x16x32_bf16 v[20:23], v[28:31], v[12:15], 0
	v_lshrrev_b32_e32 v18, 16, v18
	v_and_or_b32 v41, v19, s64, v18
	v_add_u32_e32 v18, s0, v128
	v_mfma_f32_16x16x32_bf16 v[20:23], v[36:39], v[8:11], v[20:23]
	v_ashrrev_i32_e32 v19, 31, v18
	v_lshlrev_b64 v[18:19], 9, v[18:19]
	v_lshl_add_u64 v[18:19], v[70:71], 0, v[18:19]
	global_store_dwordx2 v[18:19], v[40:41], off
	v_mfma_f32_16x16x32_bf16 v[28:31], v[28:31], v[4:7], 0
	s_nop 2
	v_bfe_u32 v40, v20, 16, 1
	v_add3_u32 v20, v20, v40, s81
	v_bfe_u32 v40, v21, 16, 1
	v_lshrrev_b32_e32 v20, 16, v20
	v_add3_u32 v21, v21, v40, s81
	v_and_or_b32 v20, v21, s64, v20
	v_bfe_u32 v21, v22, 16, 1
	v_add3_u32 v21, v22, v21, s81
	v_bfe_u32 v22, v23, 16, 1
	v_lshrrev_b32_e32 v21, 16, v21
	v_add3_u32 v22, v23, v22, s81
	v_and_or_b32 v21, v22, s64, v21
	global_store_dwordx2 v[16:17], v[20:21], off offset:32
	v_mfma_f32_16x16x32_bf16 v[20:23], v[36:39], v[0:3], v[28:31]
	s_nop 7
	v_bfe_u32 v28, v20, 16, 1
	v_add3_u32 v20, v20, v28, s81
	ds_read_b128 v[28:31], v131
	v_bfe_u32 v36, v21, 16, 1
	v_add3_u32 v21, v21, v36, s81
	ds_read_b128 v[36:39], v132
	v_lshrrev_b32_e32 v20, 16, v20
	v_and_or_b32 v20, v21, s64, v20
	v_bfe_u32 v21, v22, 16, 1
	s_waitcnt lgkmcnt(1)
	v_mfma_f32_16x16x32_bf16 v[40:43], v[28:31], v[12:15], 0
	v_add3_u32 v21, v22, v21, s81
	v_bfe_u32 v22, v23, 16, 1
	v_lshrrev_b32_e32 v21, 16, v21
	v_add3_u32 v22, v23, v22, s81
	v_and_or_b32 v21, v22, s64, v21
	global_store_dwordx2 v[18:19], v[20:21], off offset:32
	s_waitcnt lgkmcnt(0)
	v_mfma_f32_16x16x32_bf16 v[20:23], v[36:39], v[8:11], v[40:43]
	v_mfma_f32_16x16x32_bf16 v[28:31], v[28:31], v[4:7], 0
	s_nop 6
	v_bfe_u32 v40, v20, 16, 1
	v_add3_u32 v20, v20, v40, s81
	v_bfe_u32 v40, v21, 16, 1
	v_lshrrev_b32_e32 v20, 16, v20
	v_add3_u32 v21, v21, v40, s81
	v_and_or_b32 v20, v21, s64, v20
	v_bfe_u32 v21, v22, 16, 1
	v_add3_u32 v21, v22, v21, s81
	v_bfe_u32 v22, v23, 16, 1
	v_lshrrev_b32_e32 v21, 16, v21
	v_add3_u32 v22, v23, v22, s81
	v_and_or_b32 v21, v22, s64, v21
	global_store_dwordx2 v[16:17], v[20:21], off offset:64
	v_mfma_f32_16x16x32_bf16 v[20:23], v[36:39], v[0:3], v[28:31]
	s_nop 7
	v_bfe_u32 v28, v20, 16, 1
	v_add3_u32 v20, v20, v28, s81
	ds_read_b128 v[28:31], v133
	v_bfe_u32 v36, v21, 16, 1
	v_add3_u32 v21, v21, v36, s81
	ds_read_b128 v[36:39], v134
	v_lshrrev_b32_e32 v20, 16, v20
	v_and_or_b32 v20, v21, s64, v20
	v_bfe_u32 v21, v22, 16, 1
	s_waitcnt lgkmcnt(1)
	v_mfma_f32_16x16x32_bf16 v[40:43], v[28:31], v[12:15], 0
	v_add3_u32 v21, v22, v21, s81
	v_bfe_u32 v22, v23, 16, 1
	v_lshrrev_b32_e32 v21, 16, v21
	v_add3_u32 v22, v23, v22, s81
	v_and_or_b32 v21, v22, s64, v21
	global_store_dwordx2 v[18:19], v[20:21], off offset:64
	s_waitcnt lgkmcnt(0)
	v_mfma_f32_16x16x32_bf16 v[20:23], v[36:39], v[8:11], v[40:43]
	v_mfma_f32_16x16x32_bf16 v[28:31], v[28:31], v[4:7], 0
	s_nop 6
	v_bfe_u32 v40, v20, 16, 1
	v_add3_u32 v20, v20, v40, s81
	v_bfe_u32 v40, v21, 16, 1
	v_lshrrev_b32_e32 v20, 16, v20
	v_add3_u32 v21, v21, v40, s81
	v_and_or_b32 v20, v21, s64, v20
	v_bfe_u32 v21, v22, 16, 1
	v_add3_u32 v21, v22, v21, s81
	v_bfe_u32 v22, v23, 16, 1
	v_lshrrev_b32_e32 v21, 16, v21
	v_add3_u32 v22, v23, v22, s81
	v_and_or_b32 v21, v22, s64, v21
	global_store_dwordx2 v[16:17], v[20:21], off offset:96
	v_mfma_f32_16x16x32_bf16 v[20:23], v[36:39], v[0:3], v[28:31]
	s_nop 7
	v_bfe_u32 v28, v20, 16, 1
	v_add3_u32 v20, v20, v28, s81
	v_bfe_u32 v28, v21, 16, 1
	v_lshrrev_b32_e32 v20, 16, v20
	v_add3_u32 v21, v21, v28, s81
	v_and_or_b32 v20, v21, s64, v20
	v_bfe_u32 v21, v22, 16, 1
	v_mfma_f32_16x16x32_bf16 v[28:31], v[24:27], v[12:15], 0
	v_add3_u32 v21, v22, v21, s81
	v_bfe_u32 v22, v23, 16, 1
	v_lshrrev_b32_e32 v21, 16, v21
	v_add3_u32 v22, v23, v22, s81
	v_and_or_b32 v21, v22, s64, v21
	global_store_dwordx2 v[18:19], v[20:21], off offset:96
	v_mfma_f32_16x16x32_bf16 v[20:23], v[32:35], v[8:11], v[28:31]
	v_mfma_f32_16x16x32_bf16 v[24:27], v[24:27], v[4:7], 0
	s_nop 6
	v_bfe_u32 v28, v20, 16, 1
	v_add3_u32 v20, v20, v28, s81
	v_bfe_u32 v28, v21, 16, 1
	v_lshrrev_b32_e32 v20, 16, v20
	v_add3_u32 v21, v21, v28, s81
	v_and_or_b32 v20, v21, s64, v20
	v_bfe_u32 v21, v22, 16, 1
	v_add3_u32 v21, v22, v21, s81
	v_bfe_u32 v22, v23, 16, 1
	v_lshrrev_b32_e32 v21, 16, v21
	v_add3_u32 v22, v23, v22, s81
	v_and_or_b32 v21, v22, s64, v21
	global_store_dwordx2 v[16:17], v[20:21], off offset:128
	v_mfma_f32_16x16x32_bf16 v[20:23], v[32:35], v[0:3], v[24:27]
	s_nop 7
	v_bfe_u32 v24, v20, 16, 1
	v_add3_u32 v20, v20, v24, s81
	ds_read_b128 v[24:27], v135
	v_bfe_u32 v28, v21, 16, 1
	v_add3_u32 v21, v21, v28, s81
	ds_read_b128 v[28:31], v136
	v_lshrrev_b32_e32 v20, 16, v20
	v_and_or_b32 v20, v21, s64, v20
	v_bfe_u32 v21, v22, 16, 1
	s_waitcnt lgkmcnt(1)
; __device__ __forceinline__ unsigned pk2(float lo, float hi) { return f2bf(lo) | (f2bf(hi) << 16); }
; __device__ __forceinline__ float bf2f(unsigned b) { return __uint_as_float(b << 16); }
; __device__ __forceinline__ void m1_phase(const Params& p, unsigned char* ldsg, int G) {
;     ...
;                 for (int ks = 0; ks < 2; ++ks) av[mi][ks] = *(const bf16x8*)(VT + tsw(16 * (2 * hw + mi) + fr, ks * 32 + fq * 8));
; #pragma unroll
;             for (int nt = 0; nt < 8; ++nt) {
;                 bf16x8 bk[2];
; #pragma unroll
;                 for (int ks = 0; ks < 2; ++ks) bk[ks] = *(const bf16x8*)(KT + tsw(16 * nt + fr, ks * 32 + fq * 8));
; #pragma unroll
;                 for (int mi = 0; mi < 2; ++mi) {
;                     f32x4 acc = (f32x4){0.f, 0.f, 0.f, 0.f};
; #pragma unroll
;                     for (int ks = 0; ks < 2; ++ks) acc = __builtin_amdgcn_mfma_f32_16x16x32_bf16(bk[ks], av[mi][ks], acc, 0, 0, 0);
;                     u32x2 o; o.x = pk2(acc[0], acc[1]); o.y = pk2(acc[2], acc[3]);
;                     { const int vd = 16 * (2 * hw + mi) + fr; *(u32x2*)(DCB + ((size_t)((h * 64 + (vd >> 1)) * NCH + c) << 8) + (vd & 1) * 128 + 16 * nt + fq * 4) = o; }
;                 }
;             }
;             if (htid < 128) { float s = 0.f;
; #pragma unroll 8
;                 for (int l = 0; l < 64; ++l) s += bf2f(KT[htid * TP + l]);
;                 DN[(size_t)(h * NCH + c) * 128 + htid] = s; }
	v_mfma_f32_16x16x32_bf16 v[32:35], v[24:27], v[12:15], 0
	v_add3_u32 v21, v22, v21, s81
	v_bfe_u32 v22, v23, 16, 1
	v_lshrrev_b32_e32 v21, 16, v21
	v_add3_u32 v22, v23, v22, s81
	v_and_or_b32 v21, v22, s64, v21
	global_store_dwordx2 v[18:19], v[20:21], off offset:128
	s_waitcnt lgkmcnt(0)
	v_mfma_f32_16x16x32_bf16 v[20:23], v[28:31], v[8:11], v[32:35]
	v_mfma_f32_16x16x32_bf16 v[24:27], v[24:27], v[4:7], 0
	s_nop 6
	v_bfe_u32 v32, v20, 16, 1
	v_add3_u32 v20, v20, v32, s81
	v_bfe_u32 v32, v21, 16, 1
	v_lshrrev_b32_e32 v20, 16, v20
	v_add3_u32 v21, v21, v32, s81
	v_and_or_b32 v20, v21, s64, v20
	v_bfe_u32 v21, v22, 16, 1
	v_add3_u32 v21, v22, v21, s81
	v_bfe_u32 v22, v23, 16, 1
	v_lshrrev_b32_e32 v21, 16, v21
	v_add3_u32 v22, v23, v22, s81
	v_and_or_b32 v21, v22, s64, v21
	global_store_dwordx2 v[16:17], v[20:21], off offset:160
	v_mfma_f32_16x16x32_bf16 v[20:23], v[28:31], v[0:3], v[24:27]
	s_nop 7
	v_bfe_u32 v24, v20, 16, 1
	v_add3_u32 v20, v20, v24, s81
	ds_read_b128 v[24:27], v137
	v_bfe_u32 v28, v21, 16, 1
	v_add3_u32 v21, v21, v28, s81
	ds_read_b128 v[28:31], v138
	v_lshrrev_b32_e32 v20, 16, v20
	v_and_or_b32 v20, v21, s64, v20
	v_bfe_u32 v21, v22, 16, 1
	s_waitcnt lgkmcnt(1)
	v_mfma_f32_16x16x32_bf16 v[32:35], v[24:27], v[12:15], 0
	v_add3_u32 v21, v22, v21, s81
	v_bfe_u32 v22, v23, 16, 1
	v_lshrrev_b32_e32 v21, 16, v21
	v_add3_u32 v22, v23, v22, s81
	v_and_or_b32 v21, v22, s64, v21
	global_store_dwordx2 v[18:19], v[20:21], off offset:160
	s_waitcnt lgkmcnt(0)
	v_mfma_f32_16x16x32_bf16 v[20:23], v[28:31], v[8:11], v[32:35]
	v_mfma_f32_16x16x32_bf16 v[24:27], v[24:27], v[4:7], 0
	s_nop 6
	v_bfe_u32 v32, v20, 16, 1
	v_add3_u32 v20, v20, v32, s81
	v_bfe_u32 v32, v21, 16, 1
	v_lshrrev_b32_e32 v20, 16, v20
	v_add3_u32 v21, v21, v32, s81
	v_and_or_b32 v20, v21, s64, v20
	v_bfe_u32 v21, v22, 16, 1
	v_add3_u32 v21, v22, v21, s81
	v_bfe_u32 v22, v23, 16, 1
	v_lshrrev_b32_e32 v21, 16, v21
	v_add3_u32 v22, v23, v22, s81
	v_and_or_b32 v21, v22, s64, v21
	global_store_dwordx2 v[16:17], v[20:21], off offset:192
	v_mfma_f32_16x16x32_bf16 v[20:23], v[28:31], v[0:3], v[24:27]
	s_nop 7
	v_bfe_u32 v24, v20, 16, 1
	v_add3_u32 v20, v20, v24, s81
	ds_read_b128 v[24:27], v139
	v_bfe_u32 v28, v21, 16, 1
	v_add3_u32 v21, v21, v28, s81
	ds_read_b128 v[28:31], v140
	s_waitcnt lgkmcnt(1)
	v_mfma_f32_16x16x32_bf16 v[12:15], v[24:27], v[12:15], 0
	v_lshrrev_b32_e32 v20, 16, v20
	v_and_or_b32 v20, v21, s64, v20
	v_bfe_u32 v21, v22, 16, 1
	v_mfma_f32_16x16x32_bf16 v[4:7], v[24:27], v[4:7], 0
	v_add3_u32 v21, v22, v21, s81
	v_bfe_u32 v22, v23, 16, 1
	v_lshrrev_b32_e32 v21, 16, v21
	s_waitcnt lgkmcnt(0)
	v_mfma_f32_16x16x32_bf16 v[8:11], v[28:31], v[8:11], v[12:15]
	v_add3_u32 v22, v23, v22, s81
	v_and_or_b32 v21, v22, s64, v21
	global_store_dwordx2 v[18:19], v[20:21], off offset:192
	v_mfma_f32_16x16x32_bf16 v[0:3], v[28:31], v[0:3], v[4:7]
	s_nop 3
	v_bfe_u32 v12, v8, 16, 1
	s_nop 2
	v_bfe_u32 v4, v0, 16, 1
	v_add3_u32 v8, v8, v12, s81
	v_bfe_u32 v12, v9, 16, 1
	v_add3_u32 v0, v0, v4, s81
	v_bfe_u32 v4, v1, 16, 1
	v_lshrrev_b32_e32 v8, 16, v8
	v_add3_u32 v9, v9, v12, s81
	v_lshrrev_b32_e32 v0, 16, v0
	v_add3_u32 v1, v1, v4, s81
	v_and_or_b32 v8, v9, s64, v8
	v_bfe_u32 v9, v10, 16, 1
	v_and_or_b32 v0, v1, s64, v0
	v_bfe_u32 v1, v2, 16, 1
	v_add3_u32 v9, v10, v9, s81
	v_bfe_u32 v10, v11, 16, 1
	v_add3_u32 v1, v2, v1, s81
	v_bfe_u32 v2, v3, 16, 1
	v_lshrrev_b32_e32 v9, 16, v9
	v_add3_u32 v10, v11, v10, s81
	v_lshrrev_b32_e32 v1, 16, v1
	v_add3_u32 v2, v3, v2, s81
	v_and_or_b32 v9, v10, s64, v9
	v_and_or_b32 v1, v2, s64, v1
	global_store_dwordx2 v[16:17], v[8:9], off offset:224
	global_store_dwordx2 v[18:19], v[0:1], off offset:224
	s_and_saveexec_b64 s[0:1], s[20:21]
	s_cbranch_execz .LBB0_610
	v_mov_b32_e32 v0, 0
	s_mov_b32 s22, 0

; __global__ void __launch_bounds__(512, 2) fwd_megakernel(Params p) {
	.amdhsa_kernel _Z14fwd_megakernel6Params
		.amdhsa_group_segment_fixed_size 0
		.amdhsa_private_segment_fixed_size 0
		.amdhsa_kernarg_size 424
		.amdhsa_user_sgpr_count 2
		.amdhsa_user_sgpr_dispatch_ptr 0
		.amdhsa_user_sgpr_queue_ptr 0
		.amdhsa_user_sgpr_kernarg_segment_ptr 1
		.amdhsa_user_sgpr_dispatch_id 0
		.amdhsa_user_sgpr_kernarg_preload_length 0
		.amdhsa_user_sgpr_kernarg_preload_offset 0
		.amdhsa_user_sgpr_private_segment_size 0
		.amdhsa_uses_dynamic_stack 0
		.amdhsa_enable_private_segment 0
		.amdhsa_system_sgpr_workgroup_id_x 1
		.amdhsa_system_sgpr_workgroup_id_y 0
		.amdhsa_system_sgpr_workgroup_id_z 0
		.amdhsa_system_sgpr_workgroup_info 0
		.amdhsa_system_vgpr_workitem_id 2
		.amdhsa_next_free_vgpr 256
		.amdhsa_next_free_sgpr 102
		.amdhsa_accum_offset 256
		.amdhsa_reserve_vcc 1
		.amdhsa_float_round_mode_32 0
		.amdhsa_float_round_mode_16_64 0
		.amdhsa_float_denorm_mode_32 3
		.amdhsa_float_denorm_mode_16_64 3
		.amdhsa_dx10_clamp 1
		.amdhsa_ieee_mode 1
		.amdhsa_fp16_overflow 0
		.amdhsa_tg_split 0
		.amdhsa_exception_fp_ieee_invalid_op 0
		.amdhsa_exception_fp_denorm_src 0
		.amdhsa_exception_fp_ieee_div_zero 0
		.amdhsa_exception_fp_ieee_overflow 0
		.amdhsa_exception_fp_ieee_underflow 0
		.amdhsa_exception_fp_ieee_inexact 0
		.amdhsa_exception_int_div_zero 0
	.end_amdhsa_kernel

; __global__ void __launch_bounds__(512, 2) fwd_megakernel(Params p) {
amdhsa.kernels:
  - .agpr_count:     0
    .args:
      - .offset:         0
        .size:           168
        .value_kind:     by_value
      - .offset:         168
        .size:           4
        .value_kind:     hidden_block_count_x
      - .offset:         172
        .size:           4
        .value_kind:     hidden_block_count_y
      - .offset:         176
        .size:           4
        .value_kind:     hidden_block_count_z
      - .offset:         180
        .size:           2
        .value_kind:     hidden_group_size_x
      - .offset:         182
        .size:           2
        .value_kind:     hidden_group_size_y
      - .offset:         184
        .size:           2
        .value_kind:     hidden_group_size_z
      - .offset:         186
        .size:           2
        .value_kind:     hidden_remainder_x
      - .offset:         188
        .size:           2
        .value_kind:     hidden_remainder_y
      - .offset:         190
        .size:           2
        .value_kind:     hidden_remainder_z
      - .offset:         208
        .size:           8
        .value_kind:     hidden_global_offset_x
      - .offset:         216
        .size:           8
        .value_kind:     hidden_global_offset_y
      - .offset:         224
        .size:           8
        .value_kind:     hidden_global_offset_z
      - .offset:         232
        .size:           2
        .value_kind:     hidden_grid_dims
      - .offset:         256
        .size:           8
        .value_kind:     hidden_multigrid_sync_arg
      - .offset:         288
        .size:           4
        .value_kind:     hidden_dynamic_lds_size
    .group_segment_fixed_size: 0
    .kernarg_segment_align: 8
    .kernarg_segment_size: 424
    .language:       OpenCL C
    .language_version:
      - 2
      - 0
    .max_flat_workgroup_size: 512
    .name:           _Z14fwd_megakernel6Params
    .private_segment_fixed_size: 0
    .sgpr_count:     108
    .sgpr_spill_count: 18
    .symbol:         _Z14fwd_megakernel6Params.kd
    .uniform_work_group_size: 1
    .uses_dynamic_stack: false
    .vgpr_count:     256
    .vgpr_spill_count: 0
    .wavefront_size: 64
